# P4 merge-phase GEMM loops rewritten: BK=64 stages in 2x32KB LDS, full 128B-line LDS-DMA requests, XOR swizzle, all MFMAs inside the loop
# speedup vs baseline: 1.0520x; 1.0520x over previous
.LBB0_917:
	v_add_f32_e32 v82, 1.0, v247
	v_div_scale_f32 v83, s[52:53], v82, v82, 1.0
	v_rcp_f32_e32 v84, v83
	v_pk_add_f32 v[178:179], v[178:179], 1.0 op_sel_hi:[1,0]
	v_pk_add_f32 v[176:177], v[176:177], 1.0 op_sel_hi:[1,0]
	v_pk_add_f32 v[174:175], v[174:175], 1.0 op_sel_hi:[1,0]
	v_fma_f32 v85, -v83, v84, 1.0
	v_fmac_f32_e32 v84, v85, v84
	v_div_scale_f32 v85, vcc, 1.0, v82, 1.0
	v_mul_f32_e32 v86, v85, v84
	v_fma_f32 v87, -v83, v86, v85
	v_fmac_f32_e32 v86, v87, v84
	v_fma_f32 v83, -v83, v86, v85
	v_div_fmas_f32 v83, v83, v84, v86
	v_pk_add_f32 v[84:85], v[184:185], 1.0 op_sel_hi:[1,0]
	v_div_fixup_f32 v82, v83, v82, 1.0
	v_div_scale_f32 v83, s[52:53], v85, v85, 1.0
	v_rcp_f32_e32 v86, v83
	v_pk_add_f32 v[172:173], v[172:173], 1.0 op_sel_hi:[1,0]
	v_pk_add_f32 v[170:171], v[170:171], 1.0 op_sel_hi:[1,0]
	v_pk_add_f32 v[168:169], v[168:169], 1.0 op_sel_hi:[1,0]
	v_fma_f32 v87, -v83, v86, 1.0
	v_fmac_f32_e32 v86, v87, v86
	v_div_scale_f32 v87, vcc, 1.0, v85, 1.0
	v_mul_f32_e32 v88, v87, v86
	v_fma_f32 v89, -v83, v88, v87
	v_fmac_f32_e32 v88, v89, v86
	v_fma_f32 v83, -v83, v88, v87
	v_div_fmas_f32 v83, v83, v86, v88
	v_div_fixup_f32 v85, v83, v85, 1.0
	v_div_scale_f32 v83, s[52:53], v84, v84, 1.0
	v_rcp_f32_e32 v86, v83
	v_pk_add_f32 v[166:167], v[166:167], 1.0 op_sel_hi:[1,0]
	v_pk_add_f32 v[164:165], v[164:165], 1.0 op_sel_hi:[1,0]
	v_pk_add_f32 v[162:163], v[162:163], 1.0 op_sel_hi:[1,0]
	v_fma_f32 v87, -v83, v86, 1.0
	v_fmac_f32_e32 v86, v87, v86
	v_div_scale_f32 v87, vcc, 1.0, v84, 1.0
	v_mul_f32_e32 v88, v87, v86
	v_fma_f32 v89, -v83, v88, v87
	v_fmac_f32_e32 v88, v89, v86
	v_fma_f32 v83, -v83, v88, v87
	v_div_fmas_f32 v83, v83, v86, v88
	v_div_fixup_f32 v84, v83, v84, 1.0
	v_add_f32_e32 v83, 1.0, v220
	v_div_scale_f32 v86, s[52:53], v83, v83, 1.0
	v_rcp_f32_e32 v87, v86
	v_cvt_pk_bf16_f32 v220, v84, v85
	v_add_f32_e32 v84, 1.0, v246
	v_div_scale_f32 v85, s[52:53], v84, v84, 1.0
	v_fma_f32 v88, -v86, v87, 1.0
	v_fmac_f32_e32 v87, v88, v87
	v_div_scale_f32 v88, vcc, 1.0, v83, 1.0
	v_mul_f32_e32 v89, v88, v87
	v_fma_f32 v184, -v86, v89, v88
	v_fmac_f32_e32 v89, v184, v87
	v_fma_f32 v86, -v86, v89, v88
	v_div_fmas_f32 v86, v86, v87, v89
	v_div_fixup_f32 v83, v86, v83, 1.0
	v_rcp_f32_e32 v86, v85
	v_pk_add_f32 v[96:97], v[96:97], 1.0 op_sel_hi:[1,0]
	v_pk_add_f32 v[94:95], v[94:95], 1.0 op_sel_hi:[1,0]
	v_pk_add_f32 v[92:93], v[92:93], 1.0 op_sel_hi:[1,0]
	v_fma_f32 v87, -v85, v86, 1.0
	v_fmac_f32_e32 v86, v87, v86
	v_div_scale_f32 v87, vcc, 1.0, v84, 1.0
	v_mul_f32_e32 v88, v87, v86
	v_fma_f32 v89, -v85, v88, v87
	v_fmac_f32_e32 v88, v89, v86
	v_fma_f32 v85, -v85, v88, v87
	v_div_fmas_f32 v85, v85, v86, v88
	v_pk_add_f32 v[86:87], v[182:183], 1.0 op_sel_hi:[1,0]
	v_div_fixup_f32 v84, v85, v84, 1.0
	v_div_scale_f32 v85, s[52:53], v87, v87, 1.0
	v_rcp_f32_e32 v88, v85
	v_pk_add_f32 v[90:91], v[90:91], 1.0 op_sel_hi:[1,0]
	s_waitcnt lgkmcnt(0)
	v_cvt_pk_bf16_f32 v82, v82, s0
	v_fma_f32 v89, -v85, v88, 1.0
	v_fmac_f32_e32 v88, v89, v88
	v_div_scale_f32 v89, vcc, 1.0, v87, 1.0
	v_mul_f32_e32 v182, v89, v88
	v_fma_f32 v183, -v85, v182, v89
	v_fmac_f32_e32 v182, v183, v88
	v_fma_f32 v85, -v85, v182, v89
	v_div_fmas_f32 v85, v85, v88, v182
	v_div_fixup_f32 v87, v85, v87, 1.0
	v_div_scale_f32 v85, s[52:53], v86, v86, 1.0
	v_rcp_f32_e32 v88, v85
	v_cvt_pk_bf16_f32 v83, v83, s0
	v_cvt_pk_bf16_f32 v84, v84, s0
	v_fma_f32 v89, -v85, v88, 1.0
	v_fmac_f32_e32 v88, v89, v88
	v_div_scale_f32 v89, vcc, 1.0, v86, 1.0
	v_mul_f32_e32 v182, v89, v88
	v_fma_f32 v183, -v85, v182, v89
	v_fmac_f32_e32 v182, v183, v88
	v_fma_f32 v85, -v85, v182, v89
	v_div_fmas_f32 v85, v85, v88, v182
	v_div_fixup_f32 v86, v85, v86, 1.0
	v_add_f32_e32 v85, 1.0, v223
	v_div_scale_f32 v88, s[52:53], v85, v85, 1.0
	v_rcp_f32_e32 v89, v88
	v_cvt_pk_bf16_f32 v223, v86, v87
	v_add_f32_e32 v86, 1.0, v245
	v_div_scale_f32 v87, s[52:53], v86, v86, 1.0
	v_fma_f32 v182, -v88, v89, 1.0
	v_fmac_f32_e32 v89, v182, v89
	v_div_scale_f32 v182, vcc, 1.0, v85, 1.0
	v_mul_f32_e32 v183, v182, v89
	v_fma_f32 v184, -v88, v183, v182
	v_fmac_f32_e32 v183, v184, v89
	v_fma_f32 v88, -v88, v183, v182
	v_div_fmas_f32 v88, v88, v89, v183
	v_div_fixup_f32 v85, v88, v85, 1.0
	v_rcp_f32_e32 v88, v87
	v_cvt_pk_bf16_f32 v85, v85, s0
	s_add_i32 s61, s61, 1
	v_fma_f32 v89, -v87, v88, 1.0
	v_fmac_f32_e32 v88, v89, v88
	v_div_scale_f32 v89, vcc, 1.0, v86, 1.0
	v_mul_f32_e32 v182, v89, v88
	v_fma_f32 v183, -v87, v182, v89
	v_fmac_f32_e32 v182, v183, v88
	v_fma_f32 v87, -v87, v182, v89
	v_div_fmas_f32 v87, v87, v88, v182
	v_pk_add_f32 v[88:89], v[180:181], 1.0 op_sel_hi:[1,0]
	v_div_fixup_f32 v86, v87, v86, 1.0
	v_div_scale_f32 v87, s[52:53], v89, v89, 1.0
	v_rcp_f32_e32 v180, v87
	v_cvt_pk_bf16_f32 v86, v86, s0
	v_lshlrev_b32_e32 v188, 16, v86
	v_fma_f32 v181, -v87, v180, 1.0
	v_fmac_f32_e32 v180, v181, v180
	v_div_scale_f32 v181, vcc, 1.0, v89, 1.0
	v_mul_f32_e32 v182, v181, v180
	v_fma_f32 v183, -v87, v182, v181
	v_fmac_f32_e32 v182, v183, v180
	v_fma_f32 v87, -v87, v182, v181
	v_div_fmas_f32 v87, v87, v180, v182
	v_div_fixup_f32 v89, v87, v89, 1.0
	v_div_scale_f32 v87, s[52:53], v88, v88, 1.0
	v_rcp_f32_e32 v180, v87
	v_and_b32_e32 v67, 0xffff0000, v220
	v_lshlrev_b32_e32 v66, 16, v220
	v_fma_f32 v181, -v87, v180, 1.0
	v_fmac_f32_e32 v180, v181, v180
	v_div_scale_f32 v181, vcc, 1.0, v88, 1.0
	v_mul_f32_e32 v182, v181, v180
	v_fma_f32 v183, -v87, v182, v181
	v_fmac_f32_e32 v182, v183, v180
	v_fma_f32 v87, -v87, v182, v181
	v_div_fmas_f32 v87, v87, v180, v182
	v_div_fixup_f32 v88, v87, v88, 1.0
	v_add_f32_e32 v87, 1.0, v226
	v_div_scale_f32 v180, s[52:53], v87, v87, 1.0
	v_rcp_f32_e32 v181, v180
	v_cvt_pk_bf16_f32 v226, v88, v89
	v_add_f32_e32 v88, 1.0, v244
	v_div_scale_f32 v89, s[52:53], v88, v88, 1.0
	v_fma_f32 v182, -v180, v181, 1.0
	v_fmac_f32_e32 v181, v182, v181
	v_div_scale_f32 v182, vcc, 1.0, v87, 1.0
	v_mul_f32_e32 v183, v182, v181
	v_fma_f32 v184, -v180, v183, v182
	v_fmac_f32_e32 v183, v184, v181
	v_fma_f32 v180, -v180, v183, v182
	v_div_fmas_f32 v180, v180, v181, v183
	v_div_fixup_f32 v87, v180, v87, 1.0
	v_rcp_f32_e32 v180, v89
	v_cvt_pk_bf16_f32 v87, v87, s0
	v_lshlrev_b32_e32 v189, 16, v87
	s_addk_i32 s50, 0x400
	v_fma_f32 v181, -v89, v180, 1.0
	v_fmac_f32_e32 v180, v181, v180
	v_div_scale_f32 v181, vcc, 1.0, v88, 1.0
	v_mul_f32_e32 v182, v181, v180
	v_fma_f32 v183, -v89, v182, v181
	v_fmac_f32_e32 v182, v183, v180
	v_fma_f32 v89, -v89, v182, v181
	v_div_fmas_f32 v89, v89, v180, v182
	v_div_fixup_f32 v88, v89, v88, 1.0
	v_div_scale_f32 v89, s[52:53], v179, v179, 1.0
	v_rcp_f32_e32 v180, v89
	v_cvt_pk_bf16_f32 v88, v88, s0
	v_lshlrev_b32_e32 v186, 16, v88
	s_cmp_eq_u32 s61, 3
	v_fma_f32 v181, -v89, v180, 1.0
	v_fmac_f32_e32 v180, v181, v180
	v_div_scale_f32 v181, vcc, 1.0, v179, 1.0
	v_mul_f32_e32 v182, v181, v180
	v_fma_f32 v183, -v89, v182, v181
	v_fmac_f32_e32 v182, v183, v180
	v_fma_f32 v89, -v89, v182, v181
	v_div_fmas_f32 v89, v89, v180, v182
	v_div_fixup_f32 v179, v89, v179, 1.0
	v_div_scale_f32 v89, s[52:53], v178, v178, 1.0
	v_rcp_f32_e32 v180, v89
	s_nop 0
	v_fma_f32 v181, -v89, v180, 1.0
	v_fmac_f32_e32 v180, v181, v180
	v_div_scale_f32 v181, vcc, 1.0, v178, 1.0
	v_mul_f32_e32 v182, v181, v180
	v_fma_f32 v183, -v89, v182, v181
	v_fmac_f32_e32 v182, v183, v180
	v_fma_f32 v89, -v89, v182, v181
	v_div_fmas_f32 v89, v89, v180, v182
	v_div_fixup_f32 v178, v89, v178, 1.0
	v_add_f32_e32 v89, 1.0, v228
	v_div_scale_f32 v180, s[52:53], v89, v89, 1.0
	v_rcp_f32_e32 v181, v180
	v_cvt_pk_bf16_f32 v228, v178, v179
	v_add_f32_e32 v178, 1.0, v243
	v_div_scale_f32 v179, s[52:53], v178, v178, 1.0
	v_fma_f32 v182, -v180, v181, 1.0
	v_fmac_f32_e32 v181, v182, v181
	v_div_scale_f32 v182, vcc, 1.0, v89, 1.0
	v_mul_f32_e32 v183, v182, v181
	v_fma_f32 v184, -v180, v183, v182
	v_fmac_f32_e32 v183, v184, v181
	v_fma_f32 v180, -v180, v183, v182
	v_div_fmas_f32 v180, v180, v181, v183
	v_div_fixup_f32 v89, v180, v89, 1.0
	v_rcp_f32_e32 v180, v179
	v_cvt_pk_bf16_f32 v89, v89, s0
	v_lshlrev_b32_e32 v187, 16, v89
	v_fma_f32 v181, -v179, v180, 1.0
	v_fmac_f32_e32 v180, v181, v180
	v_div_scale_f32 v181, vcc, 1.0, v178, 1.0
	v_mul_f32_e32 v182, v181, v180
	v_fma_f32 v183, -v179, v182, v181
	v_fmac_f32_e32 v182, v183, v180
	v_fma_f32 v179, -v179, v182, v181
	v_div_fmas_f32 v179, v179, v180, v182
	v_div_fixup_f32 v178, v179, v178, 1.0
	v_div_scale_f32 v179, s[52:53], v177, v177, 1.0
	v_rcp_f32_e32 v180, v179
	v_cvt_pk_bf16_f32 v178, v178, s0
	v_fma_f32 v181, -v179, v180, 1.0
	v_fmac_f32_e32 v180, v181, v180
	v_div_scale_f32 v181, vcc, 1.0, v177, 1.0
	v_mul_f32_e32 v182, v181, v180
	v_fma_f32 v183, -v179, v182, v181
	v_fmac_f32_e32 v182, v183, v180
	v_fma_f32 v179, -v179, v182, v181
	v_div_fmas_f32 v179, v179, v180, v182
	v_div_fixup_f32 v177, v179, v177, 1.0
	v_div_scale_f32 v179, s[52:53], v176, v176, 1.0
	v_rcp_f32_e32 v180, v179
	s_nop 0
	v_fma_f32 v181, -v179, v180, 1.0
	v_fmac_f32_e32 v180, v181, v180
	v_div_scale_f32 v181, vcc, 1.0, v176, 1.0
	v_mul_f32_e32 v182, v181, v180
	v_fma_f32 v183, -v179, v182, v181
	v_fmac_f32_e32 v182, v183, v180
	v_fma_f32 v179, -v179, v182, v181
	v_div_fmas_f32 v179, v179, v180, v182
	v_div_fixup_f32 v179, v179, v176, 1.0
	v_add_f32_e32 v176, 1.0, v231
	v_div_scale_f32 v180, s[52:53], v176, v176, 1.0
	v_rcp_f32_e32 v181, v180
	v_cvt_pk_bf16_f32 v231, v179, v177
	v_add_f32_e32 v177, 1.0, v242
	v_div_scale_f32 v179, s[52:53], v177, v177, 1.0
	v_fma_f32 v182, -v180, v181, 1.0
	v_fmac_f32_e32 v181, v182, v181
	v_div_scale_f32 v182, vcc, 1.0, v176, 1.0
	v_mul_f32_e32 v183, v182, v181
	v_fma_f32 v184, -v180, v183, v182
	v_fmac_f32_e32 v183, v184, v181
	v_fma_f32 v180, -v180, v183, v182
	v_div_fmas_f32 v180, v180, v181, v183
	v_div_fixup_f32 v176, v180, v176, 1.0
	v_rcp_f32_e32 v180, v179
	v_cvt_pk_bf16_f32 v176, v176, s0
	v_lshlrev_b32_e32 v185, 16, v176
	v_fma_f32 v181, -v179, v180, 1.0
	v_fmac_f32_e32 v180, v181, v180
	v_div_scale_f32 v181, vcc, 1.0, v177, 1.0
	v_mul_f32_e32 v182, v181, v180
	v_fma_f32 v183, -v179, v182, v181
	v_fmac_f32_e32 v182, v183, v180
	v_fma_f32 v179, -v179, v182, v181
	v_div_fmas_f32 v179, v179, v180, v182
	v_div_fixup_f32 v177, v179, v177, 1.0
	v_div_scale_f32 v179, s[52:53], v175, v175, 1.0
	v_rcp_f32_e32 v180, v179
	v_cvt_pk_bf16_f32 v177, v177, s0
	v_fma_f32 v181, -v179, v180, 1.0
	v_fmac_f32_e32 v180, v181, v180
	v_div_scale_f32 v181, vcc, 1.0, v175, 1.0
	v_mul_f32_e32 v182, v181, v180
	v_fma_f32 v183, -v179, v182, v181
	v_fmac_f32_e32 v182, v183, v180
	v_fma_f32 v179, -v179, v182, v181
	v_div_fmas_f32 v179, v179, v180, v182
	v_div_fixup_f32 v175, v179, v175, 1.0
	v_div_scale_f32 v179, s[52:53], v174, v174, 1.0
	v_rcp_f32_e32 v180, v179
	s_nop 0
	v_fma_f32 v181, -v179, v180, 1.0
	v_fmac_f32_e32 v180, v181, v180
	v_div_scale_f32 v181, vcc, 1.0, v174, 1.0
	v_mul_f32_e32 v182, v181, v180
	v_fma_f32 v183, -v179, v182, v181
	v_fmac_f32_e32 v182, v183, v180
	v_fma_f32 v179, -v179, v182, v181
	v_div_fmas_f32 v179, v179, v180, v182
	v_div_fixup_f32 v179, v179, v174, 1.0
	v_add_f32_e32 v174, 1.0, v234
	v_div_scale_f32 v180, s[52:53], v174, v174, 1.0
	v_rcp_f32_e32 v181, v180
	v_cvt_pk_bf16_f32 v234, v179, v175
	v_add_f32_e32 v175, 1.0, v241
	v_div_scale_f32 v179, s[52:53], v175, v175, 1.0
	v_fma_f32 v182, -v180, v181, 1.0
	v_fmac_f32_e32 v181, v182, v181
	v_div_scale_f32 v182, vcc, 1.0, v174, 1.0
	v_mul_f32_e32 v183, v182, v181
	v_fma_f32 v184, -v180, v183, v182
	v_fmac_f32_e32 v183, v184, v181
	v_fma_f32 v180, -v180, v183, v182
	v_div_fmas_f32 v180, v180, v181, v183
	v_div_fixup_f32 v174, v180, v174, 1.0
	v_rcp_f32_e32 v180, v179
	v_cvt_pk_bf16_f32 v174, v174, s0
	v_fma_f32 v181, -v179, v180, 1.0
	v_fmac_f32_e32 v180, v181, v180
	v_div_scale_f32 v181, vcc, 1.0, v175, 1.0
	v_mul_f32_e32 v182, v181, v180
	v_fma_f32 v183, -v179, v182, v181
	v_fmac_f32_e32 v182, v183, v180
	v_fma_f32 v179, -v179, v182, v181
	v_div_fmas_f32 v179, v179, v180, v182
	v_div_fixup_f32 v175, v179, v175, 1.0
	v_div_scale_f32 v179, s[52:53], v173, v173, 1.0
	v_rcp_f32_e32 v180, v179
	v_cvt_pk_bf16_f32 v175, v175, s0
	v_fma_f32 v181, -v179, v180, 1.0
	v_fmac_f32_e32 v180, v181, v180
	v_div_scale_f32 v181, vcc, 1.0, v173, 1.0
	v_mul_f32_e32 v182, v181, v180
	v_fma_f32 v183, -v179, v182, v181
	v_fmac_f32_e32 v182, v183, v180
	v_fma_f32 v179, -v179, v182, v181
	v_div_fmas_f32 v179, v179, v180, v182
	v_div_fixup_f32 v173, v179, v173, 1.0
	v_div_scale_f32 v179, s[52:53], v172, v172, 1.0
	v_rcp_f32_e32 v180, v179
	s_nop 0
	v_fma_f32 v181, -v179, v180, 1.0
	v_fmac_f32_e32 v180, v181, v180
	v_div_scale_f32 v181, vcc, 1.0, v172, 1.0
	v_mul_f32_e32 v182, v181, v180
	v_fma_f32 v183, -v179, v182, v181
	v_fmac_f32_e32 v182, v183, v180
	v_fma_f32 v179, -v179, v182, v181
	v_div_fmas_f32 v179, v179, v180, v182
	v_div_fixup_f32 v179, v179, v172, 1.0
	v_add_f32_e32 v172, 1.0, v237
	v_div_scale_f32 v180, s[52:53], v172, v172, 1.0
	v_rcp_f32_e32 v181, v180
	v_cvt_pk_bf16_f32 v237, v179, v173
	v_add_f32_e32 v173, 1.0, v240
	v_div_scale_f32 v179, s[52:53], v173, v173, 1.0
	v_fma_f32 v182, -v180, v181, 1.0
	v_fmac_f32_e32 v181, v182, v181
	v_div_scale_f32 v182, vcc, 1.0, v172, 1.0
	v_mul_f32_e32 v183, v182, v181
	v_fma_f32 v184, -v180, v183, v182
	v_fmac_f32_e32 v183, v184, v181
	v_fma_f32 v180, -v180, v183, v182
	v_div_fmas_f32 v180, v180, v181, v183
	v_div_fixup_f32 v172, v180, v172, 1.0
	v_rcp_f32_e32 v180, v179
	v_cvt_pk_bf16_f32 v172, v172, s0
	v_fma_f32 v181, -v179, v180, 1.0
	v_fmac_f32_e32 v180, v181, v180
	v_div_scale_f32 v181, vcc, 1.0, v173, 1.0
	v_mul_f32_e32 v182, v181, v180
	v_fma_f32 v183, -v179, v182, v181
	v_fmac_f32_e32 v182, v183, v180
	v_fma_f32 v179, -v179, v182, v181
	v_div_fmas_f32 v179, v179, v180, v182
	v_div_fixup_f32 v173, v179, v173, 1.0
	v_div_scale_f32 v179, s[52:53], v171, v171, 1.0
	v_rcp_f32_e32 v180, v179
	v_cvt_pk_bf16_f32 v173, v173, s0
	v_fma_f32 v181, -v179, v180, 1.0
	v_fmac_f32_e32 v180, v181, v180
	v_div_scale_f32 v181, vcc, 1.0, v171, 1.0
	v_mul_f32_e32 v182, v181, v180
	v_fma_f32 v183, -v179, v182, v181
	v_fmac_f32_e32 v182, v183, v180
	v_fma_f32 v179, -v179, v182, v181
	v_div_fmas_f32 v179, v179, v180, v182
	v_div_fixup_f32 v171, v179, v171, 1.0
	v_div_scale_f32 v179, s[52:53], v170, v170, 1.0
	v_rcp_f32_e32 v180, v179
	s_nop 0
	v_fma_f32 v181, -v179, v180, 1.0
	v_fmac_f32_e32 v180, v181, v180
	v_div_scale_f32 v181, vcc, 1.0, v170, 1.0
	v_mul_f32_e32 v182, v181, v180
	v_fma_f32 v183, -v179, v182, v181
	v_fmac_f32_e32 v182, v183, v180
	v_fma_f32 v179, -v179, v182, v181
	v_div_fmas_f32 v179, v179, v180, v182
	v_div_fixup_f32 v179, v179, v170, 1.0
	v_add_f32_e32 v170, 1.0, v239
	v_div_scale_f32 v180, s[52:53], v170, v170, 1.0
	v_rcp_f32_e32 v181, v180
	v_cvt_pk_bf16_f32 v239, v179, v171
	v_add_f32_e32 v171, 1.0, v238
	v_div_scale_f32 v179, s[52:53], v171, v171, 1.0
	v_fma_f32 v182, -v180, v181, 1.0
	v_fmac_f32_e32 v181, v182, v181
	v_div_scale_f32 v182, vcc, 1.0, v170, 1.0
	v_mul_f32_e32 v183, v182, v181
	v_fma_f32 v184, -v180, v183, v182
	v_fmac_f32_e32 v183, v184, v181
	v_fma_f32 v180, -v180, v183, v182
	v_div_fmas_f32 v180, v180, v181, v183
	v_div_fixup_f32 v170, v180, v170, 1.0
	v_rcp_f32_e32 v180, v179
	v_cvt_pk_bf16_f32 v170, v170, s0
	v_fma_f32 v181, -v179, v180, 1.0
	v_fmac_f32_e32 v180, v181, v180
	v_div_scale_f32 v181, vcc, 1.0, v171, 1.0
	v_mul_f32_e32 v182, v181, v180
	v_fma_f32 v183, -v179, v182, v181
	v_fmac_f32_e32 v182, v183, v180
	v_fma_f32 v179, -v179, v182, v181
	v_div_fmas_f32 v179, v179, v180, v182
	v_div_fixup_f32 v171, v179, v171, 1.0
	v_div_scale_f32 v179, s[52:53], v169, v169, 1.0
	v_rcp_f32_e32 v180, v179
	v_cvt_pk_bf16_f32 v171, v171, s0
	v_lshlrev_b32_e32 v176, 16, v171
	v_fma_f32 v181, -v179, v180, 1.0
	v_fmac_f32_e32 v180, v181, v180
	v_div_scale_f32 v181, vcc, 1.0, v169, 1.0
	v_mul_f32_e32 v182, v181, v180
	v_fma_f32 v183, -v179, v182, v181
	v_fmac_f32_e32 v182, v183, v180
	v_fma_f32 v179, -v179, v182, v181
	v_div_fmas_f32 v179, v179, v180, v182
	v_div_fixup_f32 v169, v179, v169, 1.0
	v_div_scale_f32 v179, s[52:53], v168, v168, 1.0
	v_rcp_f32_e32 v180, v179
	s_nop 0
	v_fma_f32 v181, -v179, v180, 1.0
	v_fmac_f32_e32 v180, v181, v180
	v_div_scale_f32 v181, vcc, 1.0, v168, 1.0
	v_mul_f32_e32 v182, v181, v180
	v_fma_f32 v183, -v179, v182, v181
	v_fmac_f32_e32 v182, v183, v180
	v_fma_f32 v179, -v179, v182, v181
	v_div_fmas_f32 v179, v179, v180, v182
	v_div_fixup_f32 v179, v179, v168, 1.0
	v_add_f32_e32 v168, 1.0, v236
	v_div_scale_f32 v180, s[52:53], v168, v168, 1.0
	v_rcp_f32_e32 v181, v180
	v_cvt_pk_bf16_f32 v236, v179, v169
	v_add_f32_e32 v169, 1.0, v235
	v_div_scale_f32 v179, s[52:53], v169, v169, 1.0
	v_fma_f32 v182, -v180, v181, 1.0
	v_fmac_f32_e32 v181, v182, v181
	v_div_scale_f32 v182, vcc, 1.0, v168, 1.0
	v_mul_f32_e32 v183, v182, v181
	v_fma_f32 v184, -v180, v183, v182
	v_fmac_f32_e32 v183, v184, v181
	v_fma_f32 v180, -v180, v183, v182
	v_div_fmas_f32 v180, v180, v181, v183
	v_div_fixup_f32 v168, v180, v168, 1.0
	v_rcp_f32_e32 v180, v179
	v_cvt_pk_bf16_f32 v168, v168, s0
	v_fma_f32 v181, -v179, v180, 1.0
	v_fmac_f32_e32 v180, v181, v180
	v_div_scale_f32 v181, vcc, 1.0, v169, 1.0
	v_mul_f32_e32 v182, v181, v180
	v_fma_f32 v183, -v179, v182, v181
	v_fmac_f32_e32 v182, v183, v180
	v_fma_f32 v179, -v179, v182, v181
	v_div_fmas_f32 v179, v179, v180, v182
	v_div_fixup_f32 v169, v179, v169, 1.0
	v_div_scale_f32 v179, s[52:53], v167, v167, 1.0
	v_rcp_f32_e32 v180, v179
	v_cvt_pk_bf16_f32 v169, v169, s0
	v_fma_f32 v181, -v179, v180, 1.0
	v_fmac_f32_e32 v180, v181, v180
	v_div_scale_f32 v181, vcc, 1.0, v167, 1.0
	v_mul_f32_e32 v182, v181, v180
	v_fma_f32 v183, -v179, v182, v181
	v_fmac_f32_e32 v182, v183, v180
	v_fma_f32 v179, -v179, v182, v181
	v_div_fmas_f32 v179, v179, v180, v182
	v_div_fixup_f32 v167, v179, v167, 1.0
	v_div_scale_f32 v179, s[52:53], v166, v166, 1.0
	v_rcp_f32_e32 v180, v179
	s_nop 0
	v_fma_f32 v181, -v179, v180, 1.0
	v_fmac_f32_e32 v180, v181, v180
	v_div_scale_f32 v181, vcc, 1.0, v166, 1.0
	v_mul_f32_e32 v182, v181, v180
	v_fma_f32 v183, -v179, v182, v181
	v_fmac_f32_e32 v182, v183, v180
	v_fma_f32 v179, -v179, v182, v181
	v_div_fmas_f32 v179, v179, v180, v182
	v_div_fixup_f32 v179, v179, v166, 1.0
	v_add_f32_e32 v166, 1.0, v233
	v_div_scale_f32 v180, s[52:53], v166, v166, 1.0
	v_rcp_f32_e32 v181, v180
	v_cvt_pk_bf16_f32 v233, v179, v167
	v_add_f32_e32 v167, 1.0, v232
	v_div_scale_f32 v179, s[52:53], v167, v167, 1.0
	v_fma_f32 v182, -v180, v181, 1.0
	v_fmac_f32_e32 v181, v182, v181
	v_div_scale_f32 v182, vcc, 1.0, v166, 1.0
	v_mul_f32_e32 v183, v182, v181
	v_fma_f32 v184, -v180, v183, v182
	v_fmac_f32_e32 v183, v184, v181
	v_fma_f32 v180, -v180, v183, v182
	v_div_fmas_f32 v180, v180, v181, v183
	v_div_fixup_f32 v166, v180, v166, 1.0
	v_rcp_f32_e32 v180, v179
	v_cvt_pk_bf16_f32 v166, v166, s0
	v_fma_f32 v181, -v179, v180, 1.0
	v_fmac_f32_e32 v180, v181, v180
	v_div_scale_f32 v181, vcc, 1.0, v167, 1.0
	v_mul_f32_e32 v182, v181, v180
	v_fma_f32 v183, -v179, v182, v181
	v_fmac_f32_e32 v182, v183, v180
	v_fma_f32 v179, -v179, v182, v181
	v_div_fmas_f32 v179, v179, v180, v182
	v_div_fixup_f32 v167, v179, v167, 1.0
	v_div_scale_f32 v179, s[52:53], v165, v165, 1.0
	v_rcp_f32_e32 v180, v179
	v_cvt_pk_bf16_f32 v167, v167, s0
	v_fma_f32 v181, -v179, v180, 1.0
	v_fmac_f32_e32 v180, v181, v180
	v_div_scale_f32 v181, vcc, 1.0, v165, 1.0
	v_mul_f32_e32 v182, v181, v180
	v_fma_f32 v183, -v179, v182, v181
	v_fmac_f32_e32 v182, v183, v180
	v_fma_f32 v179, -v179, v182, v181
	v_div_fmas_f32 v179, v179, v180, v182
	v_div_fixup_f32 v165, v179, v165, 1.0
	v_div_scale_f32 v179, s[52:53], v164, v164, 1.0
	v_rcp_f32_e32 v180, v179
	s_nop 0
	v_fma_f32 v181, -v179, v180, 1.0
	v_fmac_f32_e32 v180, v181, v180
	v_div_scale_f32 v181, vcc, 1.0, v164, 1.0
	v_mul_f32_e32 v182, v181, v180
	v_fma_f32 v183, -v179, v182, v181
	v_fmac_f32_e32 v182, v183, v180
	v_fma_f32 v179, -v179, v182, v181
	v_div_fmas_f32 v179, v179, v180, v182
	v_div_fixup_f32 v179, v179, v164, 1.0
	v_add_f32_e32 v164, 1.0, v230
	v_div_scale_f32 v180, s[52:53], v164, v164, 1.0
	v_rcp_f32_e32 v181, v180
	v_cvt_pk_bf16_f32 v230, v179, v165
	v_add_f32_e32 v165, 1.0, v229
	v_div_scale_f32 v179, s[52:53], v165, v165, 1.0
	v_fma_f32 v182, -v180, v181, 1.0
	v_fmac_f32_e32 v181, v182, v181
	v_div_scale_f32 v182, vcc, 1.0, v164, 1.0
	v_mul_f32_e32 v183, v182, v181
	v_fma_f32 v184, -v180, v183, v182
	v_fmac_f32_e32 v183, v184, v181
	v_fma_f32 v180, -v180, v183, v182
	v_div_fmas_f32 v180, v180, v181, v183
	v_div_fixup_f32 v164, v180, v164, 1.0
	v_rcp_f32_e32 v180, v179
	v_cvt_pk_bf16_f32 v164, v164, s0
	v_fma_f32 v181, -v179, v180, 1.0
	v_fmac_f32_e32 v180, v181, v180
	v_div_scale_f32 v181, vcc, 1.0, v165, 1.0
	v_mul_f32_e32 v182, v181, v180
	v_fma_f32 v183, -v179, v182, v181
	v_fmac_f32_e32 v182, v183, v180
	v_fma_f32 v179, -v179, v182, v181
	v_div_fmas_f32 v179, v179, v180, v182
	v_div_fixup_f32 v165, v179, v165, 1.0
	v_div_scale_f32 v179, s[52:53], v163, v163, 1.0
	v_rcp_f32_e32 v180, v179
	v_cvt_pk_bf16_f32 v165, v165, s0
	v_fma_f32 v181, -v179, v180, 1.0
	v_fmac_f32_e32 v180, v181, v180
	v_div_scale_f32 v181, vcc, 1.0, v163, 1.0
	v_mul_f32_e32 v182, v181, v180
	v_fma_f32 v183, -v179, v182, v181
	v_fmac_f32_e32 v182, v183, v180
	v_fma_f32 v179, -v179, v182, v181
	v_div_fmas_f32 v179, v179, v180, v182
	v_div_fixup_f32 v163, v179, v163, 1.0
	v_div_scale_f32 v179, s[52:53], v162, v162, 1.0
	v_rcp_f32_e32 v180, v179
	s_nop 0
	v_fma_f32 v181, -v179, v180, 1.0
	v_fmac_f32_e32 v180, v181, v180
	v_div_scale_f32 v181, vcc, 1.0, v162, 1.0
	v_mul_f32_e32 v182, v181, v180
	v_fma_f32 v183, -v179, v182, v181
	v_fmac_f32_e32 v182, v183, v180
	v_fma_f32 v179, -v179, v182, v181
	v_div_fmas_f32 v179, v179, v180, v182
	v_div_fixup_f32 v179, v179, v162, 1.0
	v_add_f32_e32 v162, 1.0, v227
	v_div_scale_f32 v180, s[52:53], v162, v162, 1.0
	v_rcp_f32_e32 v181, v180
	v_cvt_pk_bf16_f32 v227, v179, v163
	v_add_f32_e32 v163, 1.0, v225
	v_div_scale_f32 v179, s[52:53], v163, v163, 1.0
	v_fma_f32 v182, -v180, v181, 1.0
	v_fmac_f32_e32 v181, v182, v181
	v_div_scale_f32 v182, vcc, 1.0, v162, 1.0
	v_mul_f32_e32 v183, v182, v181
	v_fma_f32 v184, -v180, v183, v182
	v_fmac_f32_e32 v183, v184, v181
	v_fma_f32 v180, -v180, v183, v182
	v_div_fmas_f32 v180, v180, v181, v183
	v_div_fixup_f32 v162, v180, v162, 1.0
	v_rcp_f32_e32 v180, v179
	v_cvt_pk_bf16_f32 v162, v162, s0
	v_lshlrev_b32_e32 v171, 16, v162
	v_fma_f32 v181, -v179, v180, 1.0
	v_fmac_f32_e32 v180, v181, v180
	v_div_scale_f32 v181, vcc, 1.0, v163, 1.0
	v_mul_f32_e32 v182, v181, v180
	v_fma_f32 v183, -v179, v182, v181
	v_fmac_f32_e32 v182, v183, v180
	v_fma_f32 v179, -v179, v182, v181
	v_div_fmas_f32 v179, v179, v180, v182
	v_div_fixup_f32 v163, v179, v163, 1.0
	v_div_scale_f32 v179, s[52:53], v97, v97, 1.0
	v_rcp_f32_e32 v180, v179
	v_cvt_pk_bf16_f32 v163, v163, s0
	v_fma_f32 v181, -v179, v180, 1.0
	v_fmac_f32_e32 v180, v181, v180
	v_div_scale_f32 v181, vcc, 1.0, v97, 1.0
	v_mul_f32_e32 v182, v181, v180
	v_fma_f32 v183, -v179, v182, v181
	v_fmac_f32_e32 v182, v183, v180
	v_fma_f32 v179, -v179, v182, v181
	v_div_fmas_f32 v179, v179, v180, v182
	v_div_fixup_f32 v97, v179, v97, 1.0
	v_div_scale_f32 v179, s[52:53], v96, v96, 1.0
	v_rcp_f32_e32 v180, v179
	s_nop 0
	v_fma_f32 v181, -v179, v180, 1.0
	v_fmac_f32_e32 v180, v181, v180
	v_div_scale_f32 v181, vcc, 1.0, v96, 1.0
	v_mul_f32_e32 v182, v181, v180
	v_fma_f32 v183, -v179, v182, v181
	v_fmac_f32_e32 v182, v183, v180
	v_fma_f32 v179, -v179, v182, v181
	v_div_fmas_f32 v179, v179, v180, v182
	v_div_fixup_f32 v179, v179, v96, 1.0
	v_add_f32_e32 v96, 1.0, v224
	v_div_scale_f32 v180, s[52:53], v96, v96, 1.0
	v_rcp_f32_e32 v181, v180
	v_cvt_pk_bf16_f32 v224, v179, v97
	v_add_f32_e32 v97, 1.0, v222
	v_div_scale_f32 v179, s[52:53], v97, v97, 1.0
	v_fma_f32 v182, -v180, v181, 1.0
	v_fmac_f32_e32 v181, v182, v181
	v_div_scale_f32 v182, vcc, 1.0, v96, 1.0
	v_mul_f32_e32 v183, v182, v181
	v_fma_f32 v184, -v180, v183, v182
	v_fmac_f32_e32 v183, v184, v181
	v_fma_f32 v180, -v180, v183, v182
	v_div_fmas_f32 v180, v180, v181, v183
	v_div_fixup_f32 v96, v180, v96, 1.0
	v_rcp_f32_e32 v180, v179
	v_cvt_pk_bf16_f32 v96, v96, s0
	v_fma_f32 v181, -v179, v180, 1.0
	v_fmac_f32_e32 v180, v181, v180
	v_div_scale_f32 v181, vcc, 1.0, v97, 1.0
	v_mul_f32_e32 v182, v181, v180
	v_fma_f32 v183, -v179, v182, v181
	v_fmac_f32_e32 v182, v183, v180
	v_fma_f32 v179, -v179, v182, v181
	v_div_fmas_f32 v179, v179, v180, v182
	v_div_fixup_f32 v97, v179, v97, 1.0
	v_div_scale_f32 v179, s[52:53], v95, v95, 1.0
	v_rcp_f32_e32 v180, v179
	v_cvt_pk_bf16_f32 v97, v97, s0
	v_fma_f32 v181, -v179, v180, 1.0
	v_fmac_f32_e32 v180, v181, v180
	v_div_scale_f32 v181, vcc, 1.0, v95, 1.0
	v_mul_f32_e32 v182, v181, v180
	v_fma_f32 v183, -v179, v182, v181
	v_fmac_f32_e32 v182, v183, v180
	v_fma_f32 v179, -v179, v182, v181
	v_div_fmas_f32 v179, v179, v180, v182
	v_div_fixup_f32 v95, v179, v95, 1.0
	v_div_scale_f32 v179, s[52:53], v94, v94, 1.0
	v_rcp_f32_e32 v180, v179
	s_nop 0
	v_fma_f32 v181, -v179, v180, 1.0
	v_fmac_f32_e32 v180, v181, v180
	v_div_scale_f32 v181, vcc, 1.0, v94, 1.0
	v_mul_f32_e32 v182, v181, v180
	v_fma_f32 v183, -v179, v182, v181
	v_fmac_f32_e32 v182, v183, v180
	v_fma_f32 v179, -v179, v182, v181
	v_div_fmas_f32 v179, v179, v180, v182
	v_div_fixup_f32 v94, v179, v94, 1.0
	v_add_f32_e32 v179, 1.0, v221
	v_div_scale_f32 v180, s[52:53], v179, v179, 1.0
	v_rcp_f32_e32 v181, v180
	v_cvt_pk_bf16_f32 v221, v94, v95
	v_add_f32_e32 v94, 1.0, v193
	v_div_scale_f32 v95, s[52:53], v94, v94, 1.0
	v_fma_f32 v182, -v180, v181, 1.0
	v_fmac_f32_e32 v181, v182, v181
	v_div_scale_f32 v182, vcc, 1.0, v179, 1.0
	v_mul_f32_e32 v183, v182, v181
	v_fma_f32 v184, -v180, v183, v182
	v_fmac_f32_e32 v183, v184, v181
	v_fma_f32 v180, -v180, v183, v182
	v_div_fmas_f32 v180, v180, v181, v183
	v_div_fixup_f32 v179, v180, v179, 1.0
	v_cvt_pk_bf16_f32 v229, v179, s0
	v_rcp_f32_e32 v179, v95
	v_lshlrev_b32_e32 v193, 16, v83
	v_lshlrev_b32_e32 v184, 16, v178
	v_lshlrev_b32_e32 v178, 16, v173
	v_fma_f32 v180, -v95, v179, 1.0
	v_fmac_f32_e32 v179, v180, v179
	v_div_scale_f32 v180, vcc, 1.0, v94, 1.0
	v_mul_f32_e32 v181, v180, v179
	v_fma_f32 v182, -v95, v181, v180
	v_fmac_f32_e32 v181, v182, v179
	v_fma_f32 v95, -v95, v181, v180
	v_div_fmas_f32 v95, v95, v179, v181
	v_div_fixup_f32 v94, v95, v94, 1.0
	v_div_scale_f32 v95, s[52:53], v93, v93, 1.0
	v_rcp_f32_e32 v179, v95
	v_cvt_pk_bf16_f32 v94, v94, s0
	v_lshlrev_b32_e32 v173, 16, v164
	v_lshlrev_b32_e32 v164, 16, v94
	v_fma_f32 v180, -v95, v179, 1.0
	v_fmac_f32_e32 v179, v180, v179
	v_div_scale_f32 v180, vcc, 1.0, v93, 1.0
	v_mul_f32_e32 v181, v180, v179
	v_fma_f32 v182, -v95, v181, v180
	v_fmac_f32_e32 v181, v182, v179
	v_fma_f32 v95, -v95, v181, v180
	v_div_fmas_f32 v95, v95, v179, v181
	v_div_fixup_f32 v93, v95, v93, 1.0
	v_div_scale_f32 v95, s[52:53], v92, v92, 1.0
	v_rcp_f32_e32 v179, v95
	s_nop 0
	v_fma_f32 v180, -v95, v179, 1.0
	v_fmac_f32_e32 v179, v180, v179
	v_div_scale_f32 v180, vcc, 1.0, v92, 1.0
	v_mul_f32_e32 v181, v180, v179
	v_fma_f32 v182, -v95, v181, v180
	v_fmac_f32_e32 v181, v182, v179
	v_fma_f32 v95, -v95, v181, v180
	v_div_fmas_f32 v95, v95, v179, v181
	v_div_fixup_f32 v92, v95, v92, 1.0
	v_add_f32_e32 v95, 1.0, v192
	v_div_scale_f32 v179, s[52:53], v95, v95, 1.0
	v_rcp_f32_e32 v180, v179
	v_cvt_pk_bf16_f32 v222, v92, v93
	v_add_f32_e32 v92, 1.0, v191
	v_div_scale_f32 v93, s[52:53], v92, v92, 1.0
	v_fma_f32 v181, -v179, v180, 1.0
	v_fmac_f32_e32 v180, v181, v180
	v_div_scale_f32 v181, vcc, 1.0, v95, 1.0
	v_mul_f32_e32 v182, v181, v180
	v_fma_f32 v183, -v179, v182, v181
	v_fmac_f32_e32 v182, v183, v180
	v_fma_f32 v179, -v179, v182, v181
	v_div_fmas_f32 v179, v179, v180, v182
	v_div_fixup_f32 v95, v179, v95, 1.0
	v_rcp_f32_e32 v179, v93
	v_cvt_pk_bf16_f32 v95, v95, s0
	v_lshlrev_b32_e32 v192, 16, v82
	v_fma_f32 v180, -v93, v179, 1.0
	v_fmac_f32_e32 v179, v180, v179
	v_div_scale_f32 v180, vcc, 1.0, v92, 1.0
	v_mul_f32_e32 v181, v180, v179
	v_fma_f32 v182, -v93, v181, v180
	v_fmac_f32_e32 v181, v182, v179
	v_fma_f32 v93, -v93, v181, v180
	v_div_fmas_f32 v93, v93, v179, v181
	v_div_fixup_f32 v92, v93, v92, 1.0
	v_div_scale_f32 v93, s[52:53], v91, v91, 1.0
	v_rcp_f32_e32 v179, v93
	v_cvt_pk_bf16_f32 v92, v92, s0
	v_lshlrev_b32_e32 v191, 16, v85
	v_lshlrev_b32_e32 v162, 16, v92
	v_fma_f32 v180, -v93, v179, 1.0
	v_fmac_f32_e32 v179, v180, v179
	v_div_scale_f32 v180, vcc, 1.0, v91, 1.0
	v_mul_f32_e32 v181, v180, v179
	v_fma_f32 v182, -v93, v181, v180
	v_fmac_f32_e32 v181, v182, v179
	v_fma_f32 v93, -v93, v181, v180
	v_div_fmas_f32 v93, v93, v179, v181
	v_div_fixup_f32 v91, v93, v91, 1.0
	v_div_scale_f32 v93, s[52:53], v90, v90, 1.0
	v_rcp_f32_e32 v179, v93
	s_nop 0
	v_fma_f32 v180, -v93, v179, 1.0
	v_fmac_f32_e32 v179, v180, v179
	v_div_scale_f32 v180, vcc, 1.0, v90, 1.0
	v_mul_f32_e32 v181, v180, v179
	v_fma_f32 v182, -v93, v181, v180
	v_fmac_f32_e32 v181, v182, v179
	v_fma_f32 v93, -v93, v181, v180
	v_div_fmas_f32 v93, v93, v179, v181
	v_div_fixup_f32 v90, v93, v90, 1.0
	v_add_f32_e32 v93, 1.0, v190
	v_div_scale_f32 v179, s[52:53], v93, v93, 1.0
	v_rcp_f32_e32 v180, v179
	v_cvt_pk_bf16_f32 v225, v90, v91
	v_lshlrev_b32_e32 v190, 16, v84
	v_fma_f32 v181, -v179, v180, 1.0
	v_fmac_f32_e32 v180, v181, v180
	v_div_scale_f32 v181, vcc, 1.0, v93, 1.0
	v_mul_f32_e32 v182, v181, v180
	v_fma_f32 v183, -v179, v182, v181
	v_fmac_f32_e32 v182, v183, v180
	v_fma_f32 v179, -v179, v182, v181
	v_div_fmas_f32 v179, v179, v180, v182
	v_div_fixup_f32 v93, v179, v93, 1.0
	v_cvt_pk_bf16_f32 v93, v93, s0
	v_lshlrev_b32_e32 v183, 16, v174
	v_lshlrev_b32_e32 v182, 16, v177
	v_lshlrev_b32_e32 v180, 16, v175
	v_lshlrev_b32_e32 v179, 16, v170
	v_lshlrev_b32_e32 v177, 16, v168
	v_lshlrev_b32_e32 v175, 16, v166
	v_lshlrev_b32_e32 v174, 16, v169
	v_lshlrev_b32_e32 v170, 16, v165
	v_lshlrev_b32_e32 v169, 16, v96
	v_lshlrev_b32_e32 v168, 16, v163
	v_lshlrev_b32_e32 v166, 16, v97
	v_lshlrev_b32_e32 v165, 16, v95
	v_lshlrev_b32_e32 v163, 16, v93
	s_waitcnt lgkmcnt(0)
	v_lshlrev_b32_e32 v181, 16, v172
	v_lshlrev_b32_e32 v172, 16, v167
	v_lshlrev_b32_e32 v167, 16, v229
	s_nop 8
	v_mov_b32_e32 v69, v52
	v_mov_b32_e32 v52, v51
	v_mov_b32_e32 v68, v50
	v_fma_f32 v158, v52, v192, v158
	v_fma_f32 v159, v53, v193, v159
	v_and_b32_e32 v51, 0xffff0000, v223
	v_lshlrev_b32_e32 v50, 16, v223
	v_mov_b32_e32 v52, v54
	v_mov_b32_e32 v53, v56
	v_fma_f32 v156, v52, v50, v156
	v_fma_f32 v157, v53, v51, v157
	v_and_b32_e32 v51, 0xffff0000, v226
	v_lshlrev_b32_e32 v50, 16, v226
	v_mov_b32_e32 v52, v58
	v_mov_b32_e32 v53, v60
	v_pk_fma_f32 v[152:153], v[52:53], v[50:51], v[152:153]
	v_and_b32_e32 v51, 0xffff0000, v228
	v_lshlrev_b32_e32 v50, 16, v228
	v_mov_b32_e32 v52, v62
	v_mov_b32_e32 v53, v64
	v_fma_f32 v138, v52, v50, v138
	v_fma_f32 v139, v53, v51, v139
	v_mov_b32_e32 v53, v36
	v_mov_b32_e32 v36, v35
	v_mov_b32_e32 v52, v34
	v_pk_fma_f32 v[144:145], v[36:37], v[184:185], v[144:145]
	v_and_b32_e32 v35, 0xffff0000, v234
	v_lshlrev_b32_e32 v34, 16, v234
	v_mov_b32_e32 v36, v38
	v_mov_b32_e32 v37, v40
	v_pk_fma_f32 v[142:143], v[36:37], v[34:35], v[142:143]
	v_and_b32_e32 v35, 0xffff0000, v237
	v_lshlrev_b32_e32 v34, 16, v237
	v_mov_b32_e32 v36, v42
	v_mov_b32_e32 v37, v44
	v_pk_fma_f32 v[136:137], v[36:37], v[34:35], v[136:137]
	v_and_b32_e32 v35, 0xffff0000, v239
	v_lshlrev_b32_e32 v34, 16, v239
	v_mov_b32_e32 v36, v46
	v_mov_b32_e32 v37, v48
	v_pk_fma_f32 v[122:123], v[36:37], v[34:35], v[122:123]
	v_mov_b32_e32 v37, v20
	v_mov_b32_e32 v20, v19
	v_mov_b32_e32 v36, v18
	v_pk_fma_f32 v[128:129], v[20:21], v[176:177], v[128:129]
	v_and_b32_e32 v19, 0xffff0000, v233
	v_lshlrev_b32_e32 v18, 16, v233
	v_mov_b32_e32 v20, v22
	v_mov_b32_e32 v21, v24
	v_pk_fma_f32 v[126:127], v[20:21], v[18:19], v[126:127]
	v_and_b32_e32 v19, 0xffff0000, v230
	v_lshlrev_b32_e32 v18, 16, v230
	v_mov_b32_e32 v20, v26
	v_mov_b32_e32 v21, v28
	v_pk_fma_f32 v[120:121], v[20:21], v[18:19], v[120:121]
	v_and_b32_e32 v19, 0xffff0000, v227
	v_lshlrev_b32_e32 v18, 16, v227
	v_mov_b32_e32 v20, v30
	v_mov_b32_e32 v21, v32
	v_pk_fma_f32 v[106:107], v[20:21], v[18:19], v[106:107]
	v_mov_b32_e32 v21, v4
	v_mov_b32_e32 v4, v3
	v_mov_b32_e32 v20, v2
	v_pk_fma_f32 v[112:113], v[4:5], v[168:169], v[112:113]
	v_and_b32_e32 v3, 0xffff0000, v221
	v_lshlrev_b32_e32 v2, 16, v221
	v_mov_b32_e32 v4, v6
	v_mov_b32_e32 v5, v8
	v_pk_fma_f32 v[110:111], v[4:5], v[2:3], v[110:111]
	v_and_b32_e32 v3, 0xffff0000, v222
	v_lshlrev_b32_e32 v2, 16, v222
	v_mov_b32_e32 v4, v10
	v_mov_b32_e32 v5, v12
	v_mov_b32_e32 v56, v55
	v_mov_b32_e32 v60, v59
	v_mov_b32_e32 v64, v63
	v_and_b32_e32 v51, 0xffff0000, v231
	v_lshlrev_b32_e32 v50, 16, v231
	v_mov_b32_e32 v40, v39
	v_mov_b32_e32 v44, v43
	v_mov_b32_e32 v48, v47
	v_and_b32_e32 v35, 0xffff0000, v236
	v_lshlrev_b32_e32 v34, 16, v236
	v_mov_b32_e32 v24, v23
	v_mov_b32_e32 v28, v27
	v_mov_b32_e32 v32, v31
	v_and_b32_e32 v19, 0xffff0000, v224
	v_lshlrev_b32_e32 v18, 16, v224
	v_mov_b32_e32 v8, v7
	v_pk_fma_f32 v[104:105], v[4:5], v[2:3], v[104:105]
	v_mov_b32_e32 v12, v11
	v_and_b32_e32 v3, 0xffff0000, v225
	v_lshlrev_b32_e32 v2, 16, v225
	v_mov_b32_e32 v4, v14
	v_mov_b32_e32 v5, v16
	v_mov_b32_e32 v16, v15
	v_pk_fma_f32 v[160:161], v[68:69], v[66:67], v[160:161]
	v_pk_fma_f32 v[154:155], v[56:57], v[190:191], v[154:155]
	v_pk_fma_f32 v[150:151], v[60:61], v[188:189], v[150:151]
	v_pk_fma_f32 v[148:149], v[64:65], v[186:187], v[148:149]
	v_pk_fma_f32 v[146:147], v[52:53], v[50:51], v[146:147]
	v_pk_fma_f32 v[140:141], v[40:41], v[182:183], v[140:141]
	v_pk_fma_f32 v[134:135], v[44:45], v[180:181], v[134:135]
	v_pk_fma_f32 v[132:133], v[48:49], v[178:179], v[132:133]
	v_pk_fma_f32 v[130:131], v[36:37], v[34:35], v[130:131]
	v_pk_fma_f32 v[124:125], v[24:25], v[174:175], v[124:125]
	v_pk_fma_f32 v[118:119], v[28:29], v[172:173], v[118:119]
	v_pk_fma_f32 v[116:117], v[32:33], v[170:171], v[116:117]
	v_pk_fma_f32 v[114:115], v[20:21], v[18:19], v[114:115]
	v_pk_fma_f32 v[108:109], v[8:9], v[166:167], v[108:109]
	v_pk_fma_f32 v[102:103], v[12:13], v[164:165], v[102:103]
	v_pk_fma_f32 v[98:99], v[4:5], v[2:3], v[98:99]
	v_pk_fma_f32 v[100:101], v[16:17], v[162:163], v[100:101]
	s_cbranch_scc1 .LBB0_915
.LBB0_918:
	s_lshl_b32 s30, s61, 10
	s_add_i32 s54, s30, s38
	s_ashr_i32 s55, s54, 31
	s_lshl_b64 s[54:55], s[54:55], 11
	s_add_u32 s100, s0, s54
	s_addc_u32 s101, s1, s55
	s_mov_b64 s[98:99], s[42:43]
	v_mov_b32_e32 v12, v199
	v_lshrrev_b32_e32 v2, 3, v12
	v_and_b32_e32 v3, 7, v12
	v_bfe_u32 v4, v12, 4, 3
	v_xor_b32_e32 v3, v3, v4
	v_lshlrev_b32_e32 v3, 4, v3
	v_lshl_or_b32 v90, v2, 11, v3
	v_add_u32_e32 v91, 0x10000, v90
	v_add_u32_e32 v92, 0x20000, v90
	v_add_u32_e32 v93, 0x30000, v90
	v_lshlrev_b32_e32 v94, 4, v12
	v_and_b32_e32 v5, 31, v12
	v_bfe_u32 v6, v12, 5, 1
	v_bfe_u32 v7, v12, 1, 3
	v_xor_b32_e32 v6, v6, v7
	v_lshlrev_b32_e32 v97, 4, v6
	v_lshlrev_b32_e32 v5, 7, v5
	v_bfe_u32 v8, v12, 7, 1
	v_bfe_u32 v9, v12, 6, 1
	v_lshl_or_b32 v95, v8, 13, v5
	v_lshl_or_b32 v96, v9, 13, v5
	v_readfirstlane_b32 s52, v94
	s_barrier
	s_add_u32 m0, s52, 0x0
	v_mov_b32_e32 v2, 0
	global_load_lds_dwordx4 v90, s[98:99]
	s_add_u32 m0, s52, 0x1000
	v_mov_b32_e32 v3, 0
	global_load_lds_dwordx4 v91, s[98:99]
	s_add_u32 m0, s52, 0x2000
	v_mov_b32_e32 v4, 0
	global_load_lds_dwordx4 v92, s[98:99]
	s_add_u32 m0, s52, 0x3000
	v_mov_b32_e32 v5, 0
	global_load_lds_dwordx4 v93, s[98:99]
	s_add_u32 m0, s52, 0x4000
	v_mov_b32_e32 v6, 0
	global_load_lds_dwordx4 v90, s[100:101]
	s_add_u32 m0, s52, 0x5000
	v_mov_b32_e32 v7, 0
	global_load_lds_dwordx4 v91, s[100:101]
	s_add_u32 m0, s52, 0x6000
	v_mov_b32_e32 v8, 0
	global_load_lds_dwordx4 v92, s[100:101]
	s_add_u32 m0, s52, 0x7000
	v_mov_b32_e32 v9, 0
	global_load_lds_dwordx4 v93, s[100:101]
	s_add_u32 s98, s98, 0x80
	s_addc_u32 s99, s99, 0
	s_add_u32 s100, s100, 0x80
	s_addc_u32 s101, s101, 0
	s_add_u32 m0, s52, 0x8000
	v_mov_b32_e32 v10, 0
	global_load_lds_dwordx4 v90, s[98:99]
	s_add_u32 m0, s52, 0x9000
	v_mov_b32_e32 v11, 0
	global_load_lds_dwordx4 v91, s[98:99]
	s_add_u32 m0, s52, 0xa000
	v_mov_b32_e32 v12, 0
	global_load_lds_dwordx4 v92, s[98:99]
	s_add_u32 m0, s52, 0xb000
	v_mov_b32_e32 v13, 0
	global_load_lds_dwordx4 v93, s[98:99]
	s_add_u32 m0, s52, 0xc000
	v_mov_b32_e32 v14, 0
	global_load_lds_dwordx4 v90, s[100:101]
	s_add_u32 m0, s52, 0xd000
	v_mov_b32_e32 v15, 0
	global_load_lds_dwordx4 v91, s[100:101]
	s_add_u32 m0, s52, 0xe000
	v_mov_b32_e32 v16, 0
	global_load_lds_dwordx4 v92, s[100:101]
	s_add_u32 m0, s52, 0xf000
	v_mov_b32_e32 v17, 0
	global_load_lds_dwordx4 v93, s[100:101]
	s_add_u32 s98, s98, 0x80
	s_addc_u32 s99, s99, 0
	s_add_u32 s100, s100, 0x80
	s_addc_u32 s101, s101, 0
	v_mov_b32_e32 v18, 0
	v_mov_b32_e32 v19, 0
	v_mov_b32_e32 v20, 0
	v_mov_b32_e32 v21, 0
	v_mov_b32_e32 v22, 0
	v_mov_b32_e32 v23, 0
	v_mov_b32_e32 v24, 0
	v_mov_b32_e32 v25, 0
	v_mov_b32_e32 v26, 0
	v_mov_b32_e32 v27, 0
	v_mov_b32_e32 v28, 0
	v_mov_b32_e32 v29, 0
	v_mov_b32_e32 v30, 0
	v_mov_b32_e32 v31, 0
	v_mov_b32_e32 v32, 0
	v_mov_b32_e32 v33, 0
	v_mov_b32_e32 v34, 0
	v_mov_b32_e32 v35, 0
	v_mov_b32_e32 v36, 0
	v_mov_b32_e32 v37, 0
	v_mov_b32_e32 v38, 0
	v_mov_b32_e32 v39, 0
	v_mov_b32_e32 v40, 0
	v_mov_b32_e32 v41, 0
	v_mov_b32_e32 v42, 0
	v_mov_b32_e32 v43, 0
	v_mov_b32_e32 v44, 0
	v_mov_b32_e32 v45, 0
	v_mov_b32_e32 v46, 0
	v_mov_b32_e32 v47, 0
	v_mov_b32_e32 v48, 0
	v_mov_b32_e32 v49, 0
	v_mov_b32_e32 v50, 0
	v_mov_b32_e32 v51, 0
	v_mov_b32_e32 v52, 0
	v_mov_b32_e32 v53, 0
	v_mov_b32_e32 v54, 0
	v_mov_b32_e32 v55, 0
	v_mov_b32_e32 v56, 0
	v_mov_b32_e32 v57, 0
	v_mov_b32_e32 v58, 0
	v_mov_b32_e32 v59, 0
	v_mov_b32_e32 v60, 0
	v_mov_b32_e32 v61, 0
	v_mov_b32_e32 v62, 0
	v_mov_b32_e32 v63, 0
	v_mov_b32_e32 v64, 0
	v_mov_b32_e32 v65, 0
	s_waitcnt vmcnt(8)
	s_barrier
	v_add_u32_e32 v66, v97, v95
	v_add_u32_e32 v70, v97, v96
	ds_read_b128 v[78:81], v66
	ds_read_b128 v[66:69], v66 offset:4096
	ds_read_b128 v[74:77], v70 offset:16384
	ds_read_b128 v[70:73], v70 offset:20480
	s_mov_b32 s51, 7
.Lp4g_loop:
	s_waitcnt lgkmcnt(0)
	v_mfma_f32_32x32x16_bf16 v[50:65], v[74:77], v[78:81], v[50:65]
	v_xor_b32_e32 v86, 0x20, v97
	v_add_u32_e32 v82, v86, v95
	v_add_u32_e32 v86, v86, v96
	v_mfma_f32_32x32x16_bf16 v[34:49], v[70:73], v[78:81], v[34:49]
	ds_read_b128 v[78:81], v82
	ds_read_b128 v[82:85], v82 offset:4096
	v_mfma_f32_32x32x16_bf16 v[18:33], v[74:77], v[66:69], v[18:33]
	ds_read_b128 v[74:77], v86 offset:16384
	ds_read_b128 v[86:89], v86 offset:20480
	v_mfma_f32_32x32x16_bf16 v[2:17], v[70:73], v[66:69], v[2:17]
	s_waitcnt lgkmcnt(0)
	v_mfma_f32_32x32x16_bf16 v[50:65], v[74:77], v[78:81], v[50:65]
	v_xor_b32_e32 v70, 0x40, v97
	v_add_u32_e32 v66, v70, v95
	v_add_u32_e32 v70, v70, v96
	v_mfma_f32_32x32x16_bf16 v[34:49], v[86:89], v[78:81], v[34:49]
	ds_read_b128 v[78:81], v66
	ds_read_b128 v[66:69], v66 offset:4096
	v_mfma_f32_32x32x16_bf16 v[18:33], v[74:77], v[82:85], v[18:33]
	ds_read_b128 v[74:77], v70 offset:16384
	ds_read_b128 v[70:73], v70 offset:20480
	v_mfma_f32_32x32x16_bf16 v[2:17], v[86:89], v[82:85], v[2:17]
	s_waitcnt lgkmcnt(0)
	v_mfma_f32_32x32x16_bf16 v[50:65], v[74:77], v[78:81], v[50:65]
	v_xor_b32_e32 v86, 0x60, v97
	v_add_u32_e32 v82, v86, v95
	v_add_u32_e32 v86, v86, v96
	v_mfma_f32_32x32x16_bf16 v[34:49], v[70:73], v[78:81], v[34:49]
	ds_read_b128 v[78:81], v82
	ds_read_b128 v[82:85], v82 offset:4096
	v_mfma_f32_32x32x16_bf16 v[18:33], v[74:77], v[66:69], v[18:33]
	ds_read_b128 v[74:77], v86 offset:16384
	ds_read_b128 v[86:89], v86 offset:20480
	v_mfma_f32_32x32x16_bf16 v[2:17], v[70:73], v[66:69], v[2:17]
	s_waitcnt vmcnt(0) lgkmcnt(0)
	s_barrier
	s_waitcnt lgkmcnt(0)
	v_mfma_f32_32x32x16_bf16 v[50:65], v[74:77], v[78:81], v[50:65]
	v_mov_b32_e32 v70, v97
	v_add_u32_e32 v66, v70, v95
	v_add_u32_e32 v70, v70, v96
	v_mfma_f32_32x32x16_bf16 v[34:49], v[86:89], v[78:81], v[34:49]
	ds_read_b128 v[78:81], v66 offset:32768
	ds_read_b128 v[66:69], v66 offset:36864
	s_add_u32 m0, s52, 0x0
	s_nop 0
	global_load_lds_dwordx4 v90, s[98:99]
	s_add_u32 m0, s52, 0x1000
	s_nop 0
	global_load_lds_dwordx4 v91, s[98:99]
	v_mfma_f32_32x32x16_bf16 v[18:33], v[74:77], v[82:85], v[18:33]
	ds_read_b128 v[74:77], v70 offset:49152
	ds_read_b128 v[70:73], v70 offset:53248
	s_add_u32 m0, s52, 0x2000
	s_nop 0
	global_load_lds_dwordx4 v92, s[98:99]
	s_add_u32 m0, s52, 0x3000
	s_nop 0
	global_load_lds_dwordx4 v93, s[98:99]
	v_mfma_f32_32x32x16_bf16 v[2:17], v[86:89], v[82:85], v[2:17]
	s_add_u32 m0, s52, 0x4000
	s_nop 0
	global_load_lds_dwordx4 v90, s[100:101]
	s_add_u32 m0, s52, 0x5000
	s_nop 0
	global_load_lds_dwordx4 v91, s[100:101]
	s_add_u32 m0, s52, 0x6000
	s_nop 0
	global_load_lds_dwordx4 v92, s[100:101]
	s_add_u32 m0, s52, 0x7000
	s_nop 0
	global_load_lds_dwordx4 v93, s[100:101]
	s_add_u32 s98, s98, 0x80
	s_addc_u32 s99, s99, 0
	s_add_u32 s100, s100, 0x80
	s_addc_u32 s101, s101, 0
	s_waitcnt lgkmcnt(0)
	v_mfma_f32_32x32x16_bf16 v[50:65], v[74:77], v[78:81], v[50:65]
	v_xor_b32_e32 v86, 0x20, v97
	v_add_u32_e32 v82, v86, v95
	v_add_u32_e32 v86, v86, v96
	v_mfma_f32_32x32x16_bf16 v[34:49], v[70:73], v[78:81], v[34:49]
	ds_read_b128 v[78:81], v82 offset:32768
	ds_read_b128 v[82:85], v82 offset:36864
	v_mfma_f32_32x32x16_bf16 v[18:33], v[74:77], v[66:69], v[18:33]
	ds_read_b128 v[74:77], v86 offset:49152
	ds_read_b128 v[86:89], v86 offset:53248
	v_mfma_f32_32x32x16_bf16 v[2:17], v[70:73], v[66:69], v[2:17]
	s_waitcnt lgkmcnt(0)
	v_mfma_f32_32x32x16_bf16 v[50:65], v[74:77], v[78:81], v[50:65]
	v_xor_b32_e32 v70, 0x40, v97
	v_add_u32_e32 v66, v70, v95
	v_add_u32_e32 v70, v70, v96
	v_mfma_f32_32x32x16_bf16 v[34:49], v[86:89], v[78:81], v[34:49]
	ds_read_b128 v[78:81], v66 offset:32768
	ds_read_b128 v[66:69], v66 offset:36864
	v_mfma_f32_32x32x16_bf16 v[18:33], v[74:77], v[82:85], v[18:33]
	ds_read_b128 v[74:77], v70 offset:49152
	ds_read_b128 v[70:73], v70 offset:53248
	v_mfma_f32_32x32x16_bf16 v[2:17], v[86:89], v[82:85], v[2:17]
	s_waitcnt lgkmcnt(0)
	v_mfma_f32_32x32x16_bf16 v[50:65], v[74:77], v[78:81], v[50:65]
	v_xor_b32_e32 v86, 0x60, v97
	v_add_u32_e32 v82, v86, v95
	v_add_u32_e32 v86, v86, v96
	v_mfma_f32_32x32x16_bf16 v[34:49], v[70:73], v[78:81], v[34:49]
	ds_read_b128 v[78:81], v82 offset:32768
	ds_read_b128 v[82:85], v82 offset:36864
	v_mfma_f32_32x32x16_bf16 v[18:33], v[74:77], v[66:69], v[18:33]
	ds_read_b128 v[74:77], v86 offset:49152
	ds_read_b128 v[86:89], v86 offset:53248
	v_mfma_f32_32x32x16_bf16 v[2:17], v[70:73], v[66:69], v[2:17]
	s_waitcnt vmcnt(0) lgkmcnt(0)
	s_barrier
	s_waitcnt lgkmcnt(0)
	v_mfma_f32_32x32x16_bf16 v[50:65], v[74:77], v[78:81], v[50:65]
	v_mov_b32_e32 v70, v97
	v_add_u32_e32 v66, v70, v95
	v_add_u32_e32 v70, v70, v96
	v_mfma_f32_32x32x16_bf16 v[34:49], v[86:89], v[78:81], v[34:49]
	ds_read_b128 v[78:81], v66
	ds_read_b128 v[66:69], v66 offset:4096
	s_add_u32 m0, s52, 0x8000
	s_nop 0
	global_load_lds_dwordx4 v90, s[98:99]
	s_add_u32 m0, s52, 0x9000
	s_nop 0
	global_load_lds_dwordx4 v91, s[98:99]
	v_mfma_f32_32x32x16_bf16 v[18:33], v[74:77], v[82:85], v[18:33]
	ds_read_b128 v[74:77], v70 offset:16384
	ds_read_b128 v[70:73], v70 offset:20480
	s_add_u32 m0, s52, 0xa000
	s_nop 0
	global_load_lds_dwordx4 v92, s[98:99]
	s_add_u32 m0, s52, 0xb000
	s_nop 0
	global_load_lds_dwordx4 v93, s[98:99]
	v_mfma_f32_32x32x16_bf16 v[2:17], v[86:89], v[82:85], v[2:17]
	s_add_u32 m0, s52, 0xc000
	s_nop 0
	global_load_lds_dwordx4 v90, s[100:101]
	s_add_u32 m0, s52, 0xd000
	s_nop 0
	global_load_lds_dwordx4 v91, s[100:101]
	s_add_u32 m0, s52, 0xe000
	s_nop 0
	global_load_lds_dwordx4 v92, s[100:101]
	s_add_u32 m0, s52, 0xf000
	s_nop 0
	global_load_lds_dwordx4 v93, s[100:101]
	s_add_u32 s98, s98, 0x80
	s_addc_u32 s99, s99, 0
	s_add_u32 s100, s100, 0x80
	s_addc_u32 s101, s101, 0
	s_sub_u32 s51, s51, 1
	s_cmp_lg_u32 s51, 0
	s_cbranch_scc1 .Lp4g_loop
	s_waitcnt lgkmcnt(0)
	v_mfma_f32_32x32x16_bf16 v[50:65], v[74:77], v[78:81], v[50:65]
	v_xor_b32_e32 v86, 0x20, v97
	v_add_u32_e32 v82, v86, v95
	v_add_u32_e32 v86, v86, v96
	v_mfma_f32_32x32x16_bf16 v[34:49], v[70:73], v[78:81], v[34:49]
	ds_read_b128 v[78:81], v82
	ds_read_b128 v[82:85], v82 offset:4096
	v_mfma_f32_32x32x16_bf16 v[18:33], v[74:77], v[66:69], v[18:33]
	ds_read_b128 v[74:77], v86 offset:16384
	ds_read_b128 v[86:89], v86 offset:20480
	v_mfma_f32_32x32x16_bf16 v[2:17], v[70:73], v[66:69], v[2:17]
	s_waitcnt lgkmcnt(0)
	v_mfma_f32_32x32x16_bf16 v[50:65], v[74:77], v[78:81], v[50:65]
	v_xor_b32_e32 v70, 0x40, v97
	v_add_u32_e32 v66, v70, v95
	v_add_u32_e32 v70, v70, v96
	v_mfma_f32_32x32x16_bf16 v[34:49], v[86:89], v[78:81], v[34:49]
	ds_read_b128 v[78:81], v66
	ds_read_b128 v[66:69], v66 offset:4096
	v_mfma_f32_32x32x16_bf16 v[18:33], v[74:77], v[82:85], v[18:33]
	ds_read_b128 v[74:77], v70 offset:16384
	ds_read_b128 v[70:73], v70 offset:20480
	v_mfma_f32_32x32x16_bf16 v[2:17], v[86:89], v[82:85], v[2:17]
	s_waitcnt lgkmcnt(0)
	v_mfma_f32_32x32x16_bf16 v[50:65], v[74:77], v[78:81], v[50:65]
	v_xor_b32_e32 v86, 0x60, v97
	v_add_u32_e32 v82, v86, v95
	v_add_u32_e32 v86, v86, v96
	v_mfma_f32_32x32x16_bf16 v[34:49], v[70:73], v[78:81], v[34:49]
	ds_read_b128 v[78:81], v82
	ds_read_b128 v[82:85], v82 offset:4096
	v_mfma_f32_32x32x16_bf16 v[18:33], v[74:77], v[66:69], v[18:33]
	ds_read_b128 v[74:77], v86 offset:16384
	ds_read_b128 v[86:89], v86 offset:20480
	v_mfma_f32_32x32x16_bf16 v[2:17], v[70:73], v[66:69], v[2:17]
	s_waitcnt vmcnt(0) lgkmcnt(0)
	s_barrier
	s_waitcnt lgkmcnt(0)
	v_mfma_f32_32x32x16_bf16 v[50:65], v[74:77], v[78:81], v[50:65]
	v_mov_b32_e32 v70, v97
	v_add_u32_e32 v66, v70, v95
	v_add_u32_e32 v70, v70, v96
	v_mfma_f32_32x32x16_bf16 v[34:49], v[86:89], v[78:81], v[34:49]
	ds_read_b128 v[78:81], v66 offset:32768
	ds_read_b128 v[66:69], v66 offset:36864
	v_mfma_f32_32x32x16_bf16 v[18:33], v[74:77], v[82:85], v[18:33]
	ds_read_b128 v[74:77], v70 offset:49152
	ds_read_b128 v[70:73], v70 offset:53248
	v_mfma_f32_32x32x16_bf16 v[2:17], v[86:89], v[82:85], v[2:17]
	s_waitcnt lgkmcnt(0)
	v_mfma_f32_32x32x16_bf16 v[50:65], v[74:77], v[78:81], v[50:65]
	v_xor_b32_e32 v86, 0x20, v97
	v_add_u32_e32 v82, v86, v95
	v_add_u32_e32 v86, v86, v96
	v_mfma_f32_32x32x16_bf16 v[34:49], v[70:73], v[78:81], v[34:49]
	ds_read_b128 v[78:81], v82 offset:32768
	ds_read_b128 v[82:85], v82 offset:36864
	v_mfma_f32_32x32x16_bf16 v[18:33], v[74:77], v[66:69], v[18:33]
	ds_read_b128 v[74:77], v86 offset:49152
	ds_read_b128 v[86:89], v86 offset:53248
	v_mfma_f32_32x32x16_bf16 v[2:17], v[70:73], v[66:69], v[2:17]
	s_waitcnt lgkmcnt(0)
	v_mfma_f32_32x32x16_bf16 v[50:65], v[74:77], v[78:81], v[50:65]
	v_xor_b32_e32 v70, 0x40, v97
	v_add_u32_e32 v66, v70, v95
	v_add_u32_e32 v70, v70, v96
	v_mfma_f32_32x32x16_bf16 v[34:49], v[86:89], v[78:81], v[34:49]
	ds_read_b128 v[78:81], v66 offset:32768
	ds_read_b128 v[66:69], v66 offset:36864
	v_mfma_f32_32x32x16_bf16 v[18:33], v[74:77], v[82:85], v[18:33]
	ds_read_b128 v[74:77], v70 offset:49152
	ds_read_b128 v[70:73], v70 offset:53248
	v_mfma_f32_32x32x16_bf16 v[2:17], v[86:89], v[82:85], v[2:17]
	s_waitcnt lgkmcnt(0)
	v_mfma_f32_32x32x16_bf16 v[50:65], v[74:77], v[78:81], v[50:65]
	v_xor_b32_e32 v86, 0x60, v97
	v_add_u32_e32 v82, v86, v95
	v_add_u32_e32 v86, v86, v96
	v_mfma_f32_32x32x16_bf16 v[34:49], v[70:73], v[78:81], v[34:49]
	ds_read_b128 v[78:81], v82 offset:32768
	ds_read_b128 v[82:85], v82 offset:36864
	v_mfma_f32_32x32x16_bf16 v[18:33], v[74:77], v[66:69], v[18:33]
	ds_read_b128 v[74:77], v86 offset:49152
	ds_read_b128 v[86:89], v86 offset:53248
	v_mfma_f32_32x32x16_bf16 v[2:17], v[70:73], v[66:69], v[2:17]
	s_waitcnt lgkmcnt(0)
	v_mfma_f32_32x32x16_bf16 v[50:65], v[74:77], v[78:81], v[50:65]
	v_mfma_f32_32x32x16_bf16 v[34:49], v[86:89], v[78:81], v[34:49]
	v_mfma_f32_32x32x16_bf16 v[18:33], v[74:77], v[82:85], v[18:33]
	v_mfma_f32_32x32x16_bf16 v[2:17], v[86:89], v[82:85], v[2:17]
	s_nop 15
.LBB0_930:
	s_waitcnt lgkmcnt(0)
	s_cmp_eq_u32 s61, 1
	s_movk_i32 s30, 0x280
	s_cselect_b32 s30, 0x180, s30
	s_cmp_eq_u32 s61, 0
	s_waitcnt lgkmcnt(0)
	s_cselect_b32 s30, 0, s30
	s_cselect_b32 s66, 12, 8
	s_lshl_b32 s30, s30, 1
	s_add_u32 s52, s59, s30
	s_addc_u32 s53, s60, 0
	s_add_u32 s54, s44, s30
	s_addc_u32 s55, s45, 0
	s_nop 3
	v_mul_f32_e32 v0, 0xbfb8aa3b, v50
	v_exp_f32_e32 v184, v0
	v_mul_f32_e32 v0, 0xbfb8aa3b, v54
	v_exp_f32_e32 v182, v0
	v_mul_f32_e32 v0, 0xbfb8aa3b, v55
	v_exp_f32_e32 v246, v0
	v_mul_f32_e32 v0, 0xbfb8aa3b, v56
	v_exp_f32_e32 v183, v0
	v_mul_f32_e32 v0, 0xbfb8aa3b, v57
	v_exp_f32_e32 v223, v0
	v_mul_f32_e32 v0, 0xbfb8aa3b, v58
	v_exp_f32_e32 v180, v0
	v_mul_f32_e32 v0, 0xbfb8aa3b, v59
	v_exp_f32_e32 v245, v0
	v_mul_f32_e32 v0, 0xbfb8aa3b, v60
	v_exp_f32_e32 v181, v0
	v_mul_f32_e32 v0, 0xbfb8aa3b, v61
	v_exp_f32_e32 v226, v0
	v_mul_f32_e32 v0, 0xbfb8aa3b, v62
	v_exp_f32_e32 v178, v0
	v_mul_f32_e32 v0, 0xbfb8aa3b, v63
	v_exp_f32_e32 v244, v0
	v_mul_f32_e32 v0, 0xbfb8aa3b, v64
	v_exp_f32_e32 v179, v0
	v_mul_f32_e32 v0, 0xbfb8aa3b, v65
	v_exp_f32_e32 v228, v0
	v_mul_f32_e32 v0, 0xbfb8aa3b, v34
	v_exp_f32_e32 v176, v0
	v_mul_f32_e32 v0, 0xbfb8aa3b, v35
	v_exp_f32_e32 v243, v0
	v_mul_f32_e32 v0, 0xbfb8aa3b, v36
	v_exp_f32_e32 v177, v0
	v_mul_f32_e32 v0, 0xbfb8aa3b, v37
	v_exp_f32_e32 v231, v0
	v_mul_f32_e32 v0, 0xbfb8aa3b, v38
	v_exp_f32_e32 v174, v0
	v_mul_f32_e32 v0, 0xbfb8aa3b, v39
	v_exp_f32_e32 v242, v0
	v_mul_f32_e32 v0, 0xbfb8aa3b, v40
	v_exp_f32_e32 v175, v0
	v_mul_f32_e32 v0, 0xbfb8aa3b, v41
	v_exp_f32_e32 v234, v0
	v_mul_f32_e32 v0, 0xbfb8aa3b, v42
	v_exp_f32_e32 v172, v0
	v_mul_f32_e32 v0, 0xbfb8aa3b, v43
	v_exp_f32_e32 v241, v0
	v_mul_f32_e32 v0, 0xbfb8aa3b, v44
	v_exp_f32_e32 v173, v0
	v_mul_f32_e32 v0, 0xbfb8aa3b, v45
	v_exp_f32_e32 v237, v0
	v_mul_f32_e32 v0, 0xbfb8aa3b, v46
	v_exp_f32_e32 v170, v0
	v_mul_f32_e32 v0, 0xbfb8aa3b, v47
	v_exp_f32_e32 v240, v0
	v_mul_f32_e32 v0, 0xbfb8aa3b, v48
	v_exp_f32_e32 v171, v0
	v_mul_f32_e32 v0, 0xbfb8aa3b, v49
	v_exp_f32_e32 v239, v0
	v_mul_f32_e32 v0, 0xbfb8aa3b, v18
	v_exp_f32_e32 v168, v0
	v_mul_f32_e32 v0, 0xbfb8aa3b, v19
	v_exp_f32_e32 v238, v0
	v_mul_f32_e32 v0, 0xbfb8aa3b, v20
	v_exp_f32_e32 v169, v0
	v_mul_f32_e32 v0, 0xbfb8aa3b, v21
	v_exp_f32_e32 v236, v0
	v_mul_f32_e32 v0, 0xbfb8aa3b, v22
	v_exp_f32_e32 v166, v0
	v_mul_f32_e32 v0, 0xbfb8aa3b, v23
	v_exp_f32_e32 v235, v0
	v_mul_f32_e32 v0, 0xbfb8aa3b, v24
	v_exp_f32_e32 v167, v0
	v_mul_f32_e32 v0, 0xbfb8aa3b, v25
	v_exp_f32_e32 v233, v0
	v_mul_f32_e32 v0, 0xbfb8aa3b, v26
	v_exp_f32_e32 v164, v0
	v_mul_f32_e32 v0, 0xbfb8aa3b, v27
	v_exp_f32_e32 v232, v0
	v_mul_f32_e32 v0, 0xbfb8aa3b, v28
	v_exp_f32_e32 v165, v0
	v_mul_f32_e32 v0, 0xbfb8aa3b, v29
	v_exp_f32_e32 v230, v0
	v_mul_f32_e32 v0, 0xbfb8aa3b, v30
	v_exp_f32_e32 v162, v0
	v_mul_f32_e32 v0, 0xbfb8aa3b, v31
	v_exp_f32_e32 v229, v0
	v_mul_f32_e32 v0, 0xbfb8aa3b, v32
	v_exp_f32_e32 v163, v0
	v_mul_f32_e32 v0, 0xbfb8aa3b, v33
	v_exp_f32_e32 v227, v0
	v_mul_f32_e32 v0, 0xbfb8aa3b, v2
	v_exp_f32_e32 v96, v0
	v_mul_f32_e32 v0, 0xbfb8aa3b, v3
	v_exp_f32_e32 v225, v0
	v_mul_f32_e32 v0, 0xbfb8aa3b, v4
	v_exp_f32_e32 v97, v0
	v_mul_f32_e32 v0, 0xbfb8aa3b, v5
	v_exp_f32_e32 v224, v0
	v_mul_f32_e32 v0, 0xbfb8aa3b, v6
	v_exp_f32_e32 v94, v0
	v_mul_f32_e32 v0, 0xbfb8aa3b, v7
	v_exp_f32_e32 v222, v0
	v_mul_f32_e32 v0, 0xbfb8aa3b, v8
	v_exp_f32_e32 v95, v0
	v_mul_f32_e32 v0, 0xbfb8aa3b, v9
	v_exp_f32_e32 v221, v0
	v_mul_f32_e32 v0, 0xbfb8aa3b, v10
	v_exp_f32_e32 v92, v0
	v_mul_f32_e32 v0, 0xbfb8aa3b, v11
	v_exp_f32_e32 v193, v0
	v_mul_f32_e32 v0, 0xbfb8aa3b, v12
	v_exp_f32_e32 v93, v0
	v_mul_f32_e32 v0, 0xbfb8aa3b, v13
	v_exp_f32_e32 v192, v0
	v_mul_f32_e32 v0, 0xbfb8aa3b, v14
	v_exp_f32_e32 v90, v0
	v_mul_f32_e32 v0, 0xbfb8aa3b, v15
	v_exp_f32_e32 v191, v0
	v_mul_f32_e32 v0, 0xbfb8aa3b, v16
	v_mov_b32_e32 v10, v199
	v_exp_f32_e32 v91, v0
	v_mul_f32_e32 v0, 0xbfb8aa3b, v17
	v_exp_f32_e32 v190, v0
	v_mul_f32_e32 v50, 0xbfb8aa3b, v51
	v_mul_f32_e32 v51, 0xbfb8aa3b, v52
	v_mul_f32_e32 v52, 0xbfb8aa3b, v53
	v_exp_f32_e32 v247, v50
	v_exp_f32_e32 v185, v51
	v_exp_f32_e32 v220, v52
	s_add_u32 s98, s48, s30
	s_addc_u32 s99, s49, 0
	s_add_u32 s100, s44, s30
	s_addc_u32 s101, s45, 0
	s_lshr_b32 s51, s66, 2
	s_sub_u32 s51, s51, 1
	v_mov_b32_e32 v12, v199
	v_lshrrev_b32_e32 v2, 3, v12
	v_and_b32_e32 v3, 7, v12
	v_bfe_u32 v4, v12, 4, 3
	v_xor_b32_e32 v3, v3, v4
	v_lshlrev_b32_e32 v3, 4, v3
	v_mul_u32_u24_e32 v2, 0x700, v2
	v_add_u32_e32 v186, v2, v3
	v_add_u32_e32 v187, 0xe000, v186
	v_add_u32_e32 v188, 0x1c000, v186
	v_add_u32_e32 v189, 0x2a000, v186
	v_lshlrev_b32_e32 v248, 4, v12
	v_and_b32_e32 v5, 31, v12
	v_bfe_u32 v6, v12, 5, 1
	v_bfe_u32 v7, v12, 1, 3
	v_xor_b32_e32 v6, v6, v7
	v_lshlrev_b32_e32 v249, 4, v6
	v_lshlrev_b32_e32 v5, 7, v5
	v_bfe_u32 v8, v12, 7, 1
	v_bfe_u32 v9, v12, 6, 1
	v_lshl_or_b32 v201, v8, 13, v5
	v_lshl_or_b32 v202, v9, 13, v5
	v_readfirstlane_b32 s52, v248
	s_waitcnt vmcnt(0)
	s_barrier
	s_add_u32 m0, s52, 0x0
	v_mov_b32_e32 v2, 0
	global_load_lds_dwordx4 v186, s[98:99]
	s_add_u32 m0, s52, 0x1000
	v_mov_b32_e32 v3, 0
	global_load_lds_dwordx4 v187, s[98:99]
	s_add_u32 m0, s52, 0x2000
	v_mov_b32_e32 v4, 0
	global_load_lds_dwordx4 v188, s[98:99]
	s_add_u32 m0, s52, 0x3000
	v_mov_b32_e32 v5, 0
	global_load_lds_dwordx4 v189, s[98:99]
	s_add_u32 m0, s52, 0x4000
	v_mov_b32_e32 v6, 0
	global_load_lds_dwordx4 v186, s[100:101]
	s_add_u32 m0, s52, 0x5000
	v_mov_b32_e32 v7, 0
	global_load_lds_dwordx4 v187, s[100:101]
	s_add_u32 m0, s52, 0x6000
	v_mov_b32_e32 v8, 0
	global_load_lds_dwordx4 v188, s[100:101]
	s_add_u32 m0, s52, 0x7000
	v_mov_b32_e32 v9, 0
	global_load_lds_dwordx4 v189, s[100:101]
	s_add_u32 s98, s98, 0x80
	s_addc_u32 s99, s99, 0
	s_add_u32 s100, s100, 0x80
	s_addc_u32 s101, s101, 0
	s_add_u32 m0, s52, 0x8000
	v_mov_b32_e32 v10, 0
	global_load_lds_dwordx4 v186, s[98:99]
	s_add_u32 m0, s52, 0x9000
	v_mov_b32_e32 v11, 0
	global_load_lds_dwordx4 v187, s[98:99]
	s_add_u32 m0, s52, 0xa000
	v_mov_b32_e32 v12, 0
	global_load_lds_dwordx4 v188, s[98:99]
	s_add_u32 m0, s52, 0xb000
	v_mov_b32_e32 v13, 0
	global_load_lds_dwordx4 v189, s[98:99]
	s_add_u32 m0, s52, 0xc000
	v_mov_b32_e32 v14, 0
	global_load_lds_dwordx4 v186, s[100:101]
	s_add_u32 m0, s52, 0xd000
	v_mov_b32_e32 v15, 0
	global_load_lds_dwordx4 v187, s[100:101]
	s_add_u32 m0, s52, 0xe000
	v_mov_b32_e32 v16, 0
	global_load_lds_dwordx4 v188, s[100:101]
	s_add_u32 m0, s52, 0xf000
	v_mov_b32_e32 v17, 0
	global_load_lds_dwordx4 v189, s[100:101]
	s_add_u32 s98, s98, 0x80
	s_addc_u32 s99, s99, 0
	s_add_u32 s100, s100, 0x80
	s_addc_u32 s101, s101, 0
	v_mov_b32_e32 v18, 0
	v_mov_b32_e32 v19, 0
	v_mov_b32_e32 v20, 0
	v_mov_b32_e32 v21, 0
	v_mov_b32_e32 v22, 0
	v_mov_b32_e32 v23, 0
	v_mov_b32_e32 v24, 0
	v_mov_b32_e32 v25, 0
	v_mov_b32_e32 v26, 0
	v_mov_b32_e32 v27, 0
	v_mov_b32_e32 v28, 0
	v_mov_b32_e32 v29, 0
	v_mov_b32_e32 v30, 0
	v_mov_b32_e32 v31, 0
	v_mov_b32_e32 v32, 0
	v_mov_b32_e32 v33, 0
	v_mov_b32_e32 v34, 0
	v_mov_b32_e32 v35, 0
	v_mov_b32_e32 v36, 0
	v_mov_b32_e32 v37, 0
	v_mov_b32_e32 v38, 0
	v_mov_b32_e32 v39, 0
	v_mov_b32_e32 v40, 0
	v_mov_b32_e32 v41, 0
	v_mov_b32_e32 v42, 0
	v_mov_b32_e32 v43, 0
	v_mov_b32_e32 v44, 0
	v_mov_b32_e32 v45, 0
	v_mov_b32_e32 v46, 0
	v_mov_b32_e32 v47, 0
	v_mov_b32_e32 v48, 0
	v_mov_b32_e32 v49, 0
	v_mov_b32_e32 v50, 0
	v_mov_b32_e32 v51, 0
	v_mov_b32_e32 v52, 0
	v_mov_b32_e32 v53, 0
	v_mov_b32_e32 v54, 0
	v_mov_b32_e32 v55, 0
	v_mov_b32_e32 v56, 0
	v_mov_b32_e32 v57, 0
	v_mov_b32_e32 v58, 0
	v_mov_b32_e32 v59, 0
	v_mov_b32_e32 v60, 0
	v_mov_b32_e32 v61, 0
	v_mov_b32_e32 v62, 0
	v_mov_b32_e32 v63, 0
	v_mov_b32_e32 v64, 0
	v_mov_b32_e32 v65, 0
	s_waitcnt vmcnt(8)
	s_barrier
	v_add_u32_e32 v66, v249, v201
	v_add_u32_e32 v70, v249, v202
	ds_read_b128 v[78:81], v66
	ds_read_b128 v[66:69], v66 offset:4096
	ds_read_b128 v[74:77], v70 offset:16384
	ds_read_b128 v[70:73], v70 offset:20480
.Lp4b_loop:
	s_waitcnt lgkmcnt(0)
	v_mfma_f32_32x32x16_bf16 v[50:65], v[74:77], v[78:81], v[50:65]
	v_xor_b32_e32 v86, 0x20, v249
	v_add_u32_e32 v82, v86, v201
	v_add_u32_e32 v86, v86, v202
	v_mfma_f32_32x32x16_bf16 v[34:49], v[70:73], v[78:81], v[34:49]
	ds_read_b128 v[78:81], v82
	ds_read_b128 v[82:85], v82 offset:4096
	v_mfma_f32_32x32x16_bf16 v[18:33], v[74:77], v[66:69], v[18:33]
	ds_read_b128 v[74:77], v86 offset:16384
	ds_read_b128 v[86:89], v86 offset:20480
	v_mfma_f32_32x32x16_bf16 v[2:17], v[70:73], v[66:69], v[2:17]
	s_waitcnt lgkmcnt(0)
	v_mfma_f32_32x32x16_bf16 v[50:65], v[74:77], v[78:81], v[50:65]
	v_xor_b32_e32 v70, 0x40, v249
	v_add_u32_e32 v66, v70, v201
	v_add_u32_e32 v70, v70, v202
	v_mfma_f32_32x32x16_bf16 v[34:49], v[86:89], v[78:81], v[34:49]
	ds_read_b128 v[78:81], v66
	ds_read_b128 v[66:69], v66 offset:4096
	v_mfma_f32_32x32x16_bf16 v[18:33], v[74:77], v[82:85], v[18:33]
	ds_read_b128 v[74:77], v70 offset:16384
	ds_read_b128 v[70:73], v70 offset:20480
	v_mfma_f32_32x32x16_bf16 v[2:17], v[86:89], v[82:85], v[2:17]
	s_waitcnt lgkmcnt(0)
	v_mfma_f32_32x32x16_bf16 v[50:65], v[74:77], v[78:81], v[50:65]
	v_xor_b32_e32 v86, 0x60, v249
	v_add_u32_e32 v82, v86, v201
	v_add_u32_e32 v86, v86, v202
	v_mfma_f32_32x32x16_bf16 v[34:49], v[70:73], v[78:81], v[34:49]
	ds_read_b128 v[78:81], v82
	ds_read_b128 v[82:85], v82 offset:4096
	v_mfma_f32_32x32x16_bf16 v[18:33], v[74:77], v[66:69], v[18:33]
	ds_read_b128 v[74:77], v86 offset:16384
	ds_read_b128 v[86:89], v86 offset:20480
	v_mfma_f32_32x32x16_bf16 v[2:17], v[70:73], v[66:69], v[2:17]
	s_waitcnt vmcnt(0) lgkmcnt(0)
	s_barrier
	s_waitcnt lgkmcnt(0)
	v_mfma_f32_32x32x16_bf16 v[50:65], v[74:77], v[78:81], v[50:65]
	v_mov_b32_e32 v70, v249
	v_add_u32_e32 v66, v70, v201
	v_add_u32_e32 v70, v70, v202
	v_mfma_f32_32x32x16_bf16 v[34:49], v[86:89], v[78:81], v[34:49]
	ds_read_b128 v[78:81], v66 offset:32768
	ds_read_b128 v[66:69], v66 offset:36864
	s_add_u32 m0, s52, 0x0
	s_nop 0
	global_load_lds_dwordx4 v186, s[98:99]
	s_add_u32 m0, s52, 0x1000
	s_nop 0
	global_load_lds_dwordx4 v187, s[98:99]
	v_mfma_f32_32x32x16_bf16 v[18:33], v[74:77], v[82:85], v[18:33]
	ds_read_b128 v[74:77], v70 offset:49152
	ds_read_b128 v[70:73], v70 offset:53248
	s_add_u32 m0, s52, 0x2000
	s_nop 0
	global_load_lds_dwordx4 v188, s[98:99]
	s_add_u32 m0, s52, 0x3000
	s_nop 0
	global_load_lds_dwordx4 v189, s[98:99]
	v_mfma_f32_32x32x16_bf16 v[2:17], v[86:89], v[82:85], v[2:17]
	s_add_u32 m0, s52, 0x4000
	s_nop 0
	global_load_lds_dwordx4 v186, s[100:101]
	s_add_u32 m0, s52, 0x5000
	s_nop 0
	global_load_lds_dwordx4 v187, s[100:101]
	s_add_u32 m0, s52, 0x6000
	s_nop 0
	global_load_lds_dwordx4 v188, s[100:101]
	s_add_u32 m0, s52, 0x7000
	s_nop 0
	global_load_lds_dwordx4 v189, s[100:101]
	s_add_u32 s98, s98, 0x80
	s_addc_u32 s99, s99, 0
	s_add_u32 s100, s100, 0x80
	s_addc_u32 s101, s101, 0
	s_waitcnt lgkmcnt(0)
	v_mfma_f32_32x32x16_bf16 v[50:65], v[74:77], v[78:81], v[50:65]
	v_xor_b32_e32 v86, 0x20, v249
	v_add_u32_e32 v82, v86, v201
	v_add_u32_e32 v86, v86, v202
	v_mfma_f32_32x32x16_bf16 v[34:49], v[70:73], v[78:81], v[34:49]
	ds_read_b128 v[78:81], v82 offset:32768
	ds_read_b128 v[82:85], v82 offset:36864
	v_mfma_f32_32x32x16_bf16 v[18:33], v[74:77], v[66:69], v[18:33]
	ds_read_b128 v[74:77], v86 offset:49152
	ds_read_b128 v[86:89], v86 offset:53248
	v_mfma_f32_32x32x16_bf16 v[2:17], v[70:73], v[66:69], v[2:17]
	s_waitcnt lgkmcnt(0)
	v_mfma_f32_32x32x16_bf16 v[50:65], v[74:77], v[78:81], v[50:65]
	v_xor_b32_e32 v70, 0x40, v249
	v_add_u32_e32 v66, v70, v201
	v_add_u32_e32 v70, v70, v202
	v_mfma_f32_32x32x16_bf16 v[34:49], v[86:89], v[78:81], v[34:49]
	ds_read_b128 v[78:81], v66 offset:32768
	ds_read_b128 v[66:69], v66 offset:36864
	v_mfma_f32_32x32x16_bf16 v[18:33], v[74:77], v[82:85], v[18:33]
	ds_read_b128 v[74:77], v70 offset:49152
	ds_read_b128 v[70:73], v70 offset:53248
	v_mfma_f32_32x32x16_bf16 v[2:17], v[86:89], v[82:85], v[2:17]
	s_waitcnt lgkmcnt(0)
	v_mfma_f32_32x32x16_bf16 v[50:65], v[74:77], v[78:81], v[50:65]
	v_xor_b32_e32 v86, 0x60, v249
	v_add_u32_e32 v82, v86, v201
	v_add_u32_e32 v86, v86, v202
	v_mfma_f32_32x32x16_bf16 v[34:49], v[70:73], v[78:81], v[34:49]
	ds_read_b128 v[78:81], v82 offset:32768
	ds_read_b128 v[82:85], v82 offset:36864
	v_mfma_f32_32x32x16_bf16 v[18:33], v[74:77], v[66:69], v[18:33]
	ds_read_b128 v[74:77], v86 offset:49152
	ds_read_b128 v[86:89], v86 offset:53248
	v_mfma_f32_32x32x16_bf16 v[2:17], v[70:73], v[66:69], v[2:17]
	s_waitcnt vmcnt(0) lgkmcnt(0)
	s_barrier
	s_waitcnt lgkmcnt(0)
	v_mfma_f32_32x32x16_bf16 v[50:65], v[74:77], v[78:81], v[50:65]
	v_mov_b32_e32 v70, v249
	v_add_u32_e32 v66, v70, v201
	v_add_u32_e32 v70, v70, v202
	v_mfma_f32_32x32x16_bf16 v[34:49], v[86:89], v[78:81], v[34:49]
	ds_read_b128 v[78:81], v66
	ds_read_b128 v[66:69], v66 offset:4096
	s_add_u32 m0, s52, 0x8000
	s_nop 0
	global_load_lds_dwordx4 v186, s[98:99]
	s_add_u32 m0, s52, 0x9000
	s_nop 0
	global_load_lds_dwordx4 v187, s[98:99]
	v_mfma_f32_32x32x16_bf16 v[18:33], v[74:77], v[82:85], v[18:33]
	ds_read_b128 v[74:77], v70 offset:16384
	ds_read_b128 v[70:73], v70 offset:20480
	s_add_u32 m0, s52, 0xa000
	s_nop 0
	global_load_lds_dwordx4 v188, s[98:99]
	s_add_u32 m0, s52, 0xb000
	s_nop 0
	global_load_lds_dwordx4 v189, s[98:99]
	v_mfma_f32_32x32x16_bf16 v[2:17], v[86:89], v[82:85], v[2:17]
	s_add_u32 m0, s52, 0xc000
	s_nop 0
	global_load_lds_dwordx4 v186, s[100:101]
	s_add_u32 m0, s52, 0xd000
	s_nop 0
	global_load_lds_dwordx4 v187, s[100:101]
	s_add_u32 m0, s52, 0xe000
	s_nop 0
	global_load_lds_dwordx4 v188, s[100:101]
	s_add_u32 m0, s52, 0xf000
	s_nop 0
	global_load_lds_dwordx4 v189, s[100:101]
	s_add_u32 s98, s98, 0x80
	s_addc_u32 s99, s99, 0
	s_add_u32 s100, s100, 0x80
	s_addc_u32 s101, s101, 0
	s_sub_u32 s51, s51, 1
	s_cmp_lg_u32 s51, 0
	s_cbranch_scc1 .Lp4b_loop
	s_waitcnt lgkmcnt(0)
	v_mfma_f32_32x32x16_bf16 v[50:65], v[74:77], v[78:81], v[50:65]
	v_xor_b32_e32 v86, 0x20, v249
	v_add_u32_e32 v82, v86, v201
	v_add_u32_e32 v86, v86, v202
	v_mfma_f32_32x32x16_bf16 v[34:49], v[70:73], v[78:81], v[34:49]
	ds_read_b128 v[78:81], v82
	ds_read_b128 v[82:85], v82 offset:4096
	v_mfma_f32_32x32x16_bf16 v[18:33], v[74:77], v[66:69], v[18:33]
	ds_read_b128 v[74:77], v86 offset:16384
	ds_read_b128 v[86:89], v86 offset:20480
	v_mfma_f32_32x32x16_bf16 v[2:17], v[70:73], v[66:69], v[2:17]
	s_waitcnt lgkmcnt(0)
	v_mfma_f32_32x32x16_bf16 v[50:65], v[74:77], v[78:81], v[50:65]
	v_xor_b32_e32 v70, 0x40, v249
	v_add_u32_e32 v66, v70, v201
	v_add_u32_e32 v70, v70, v202
	v_mfma_f32_32x32x16_bf16 v[34:49], v[86:89], v[78:81], v[34:49]
	ds_read_b128 v[78:81], v66
	ds_read_b128 v[66:69], v66 offset:4096
	v_mfma_f32_32x32x16_bf16 v[18:33], v[74:77], v[82:85], v[18:33]
	ds_read_b128 v[74:77], v70 offset:16384
	ds_read_b128 v[70:73], v70 offset:20480
	v_mfma_f32_32x32x16_bf16 v[2:17], v[86:89], v[82:85], v[2:17]
	s_waitcnt lgkmcnt(0)
	v_mfma_f32_32x32x16_bf16 v[50:65], v[74:77], v[78:81], v[50:65]
	v_xor_b32_e32 v86, 0x60, v249
	v_add_u32_e32 v82, v86, v201
	v_add_u32_e32 v86, v86, v202
	v_mfma_f32_32x32x16_bf16 v[34:49], v[70:73], v[78:81], v[34:49]
	ds_read_b128 v[78:81], v82
	ds_read_b128 v[82:85], v82 offset:4096
	v_mfma_f32_32x32x16_bf16 v[18:33], v[74:77], v[66:69], v[18:33]
	ds_read_b128 v[74:77], v86 offset:16384
	ds_read_b128 v[86:89], v86 offset:20480
	v_mfma_f32_32x32x16_bf16 v[2:17], v[70:73], v[66:69], v[2:17]
	s_waitcnt vmcnt(0) lgkmcnt(0)
	s_barrier
	s_waitcnt lgkmcnt(0)
	v_mfma_f32_32x32x16_bf16 v[50:65], v[74:77], v[78:81], v[50:65]
	v_mov_b32_e32 v70, v249
	v_add_u32_e32 v66, v70, v201
	v_add_u32_e32 v70, v70, v202
	v_mfma_f32_32x32x16_bf16 v[34:49], v[86:89], v[78:81], v[34:49]
	ds_read_b128 v[78:81], v66 offset:32768
	ds_read_b128 v[66:69], v66 offset:36864
	v_mfma_f32_32x32x16_bf16 v[18:33], v[74:77], v[82:85], v[18:33]
	ds_read_b128 v[74:77], v70 offset:49152
	ds_read_b128 v[70:73], v70 offset:53248
	v_mfma_f32_32x32x16_bf16 v[2:17], v[86:89], v[82:85], v[2:17]
	s_waitcnt lgkmcnt(0)
	v_mfma_f32_32x32x16_bf16 v[50:65], v[74:77], v[78:81], v[50:65]
	v_xor_b32_e32 v86, 0x20, v249
	v_add_u32_e32 v82, v86, v201
	v_add_u32_e32 v86, v86, v202
	v_mfma_f32_32x32x16_bf16 v[34:49], v[70:73], v[78:81], v[34:49]
	ds_read_b128 v[78:81], v82 offset:32768
	ds_read_b128 v[82:85], v82 offset:36864
	v_mfma_f32_32x32x16_bf16 v[18:33], v[74:77], v[66:69], v[18:33]
	ds_read_b128 v[74:77], v86 offset:49152
	ds_read_b128 v[86:89], v86 offset:53248
	v_mfma_f32_32x32x16_bf16 v[2:17], v[70:73], v[66:69], v[2:17]
	s_waitcnt lgkmcnt(0)
	v_mfma_f32_32x32x16_bf16 v[50:65], v[74:77], v[78:81], v[50:65]
	v_xor_b32_e32 v70, 0x40, v249
	v_add_u32_e32 v66, v70, v201
	v_add_u32_e32 v70, v70, v202
	v_mfma_f32_32x32x16_bf16 v[34:49], v[86:89], v[78:81], v[34:49]
	ds_read_b128 v[78:81], v66 offset:32768
	ds_read_b128 v[66:69], v66 offset:36864
	v_mfma_f32_32x32x16_bf16 v[18:33], v[74:77], v[82:85], v[18:33]
	ds_read_b128 v[74:77], v70 offset:49152
	ds_read_b128 v[70:73], v70 offset:53248
	v_mfma_f32_32x32x16_bf16 v[2:17], v[86:89], v[82:85], v[2:17]
	s_waitcnt lgkmcnt(0)
	v_mfma_f32_32x32x16_bf16 v[50:65], v[74:77], v[78:81], v[50:65]
	v_xor_b32_e32 v86, 0x60, v249
	v_add_u32_e32 v82, v86, v201
	v_add_u32_e32 v86, v86, v202
	v_mfma_f32_32x32x16_bf16 v[34:49], v[70:73], v[78:81], v[34:49]
	ds_read_b128 v[78:81], v82 offset:32768
	ds_read_b128 v[82:85], v82 offset:36864
	v_mfma_f32_32x32x16_bf16 v[18:33], v[74:77], v[66:69], v[18:33]
	ds_read_b128 v[74:77], v86 offset:49152
	ds_read_b128 v[86:89], v86 offset:53248
	v_mfma_f32_32x32x16_bf16 v[2:17], v[70:73], v[66:69], v[2:17]
	s_waitcnt lgkmcnt(0)
	v_mfma_f32_32x32x16_bf16 v[50:65], v[74:77], v[78:81], v[50:65]
	v_mfma_f32_32x32x16_bf16 v[34:49], v[86:89], v[78:81], v[34:49]
	v_mfma_f32_32x32x16_bf16 v[18:33], v[74:77], v[82:85], v[18:33]
	v_mfma_f32_32x32x16_bf16 v[2:17], v[86:89], v[82:85], v[2:17]
	s_nop 15
	s_branch .LBB0_917
